# RWKV step: operand LDS reads grouped eight per two steps (8 record register sets)
# speedup vs baseline: 1.0217x; 1.0217x over previous
; DEVINL u16 f2bf(float a) { return (u16)(pk2(a, 0.f) & 0xffffu); }
; #define RW_STEP2(B) RW_STEP(B, WvA, XA, KrA, vhA, WvB, XB, KrB, vhB); RW_STEP((B) + 1, WvB, XB, KrB, vhB, WvA, XA, KrA, vhA)
; #define RW_STEP4(B) RW_STEP2(B); RW_STEP2((B) + 2)
; template <int DIR>
; DEVINL void rwkv_scan_dir(const Params& p, int task, int lane, int wave) {
;     ...
;   for (int st = 0; st < 4096; st += 32) {
;     RW_STEP(0, WvA, XA, KrA, vhA, WvB, XB, KrB, vhB);
;     if (st > 0) { const int q0 = st - 16 + seg; yo[(long)(DIR ? (4095 - q0) : q0) * 1024] = f2bf(ykeep); }
;     RW_STEP(1, WvB, XB, KrB, vhB, WvA, XA, KrA, vhA);
;     RW_STEP2(2); RW_STEP4(4); RW_STEP4(8); RW_STEP4(12);
;     RW_STEP(16, WvA, XA, KrA, vhA, WvB, XB, KrB, vhB);
;     { const int q0 = st + seg; yo[(long)(DIR ? (4095 - q0) : q0) * 1024] = f2bf(ykeep); }
.Lrw_ready_d0:
	s_add_u32 s3, s40, s41
	s_and_b32 s3, s3, 0x1ffff
	s_add_u32 s3, s3, 16
	s_mov_b32 m0, s3
	s_nop 0
	global_load_lds_dwordx4 v5, s[10:11] offset:0
	global_load_lds_dwordx4 v5, s[10:11] offset:1024
	global_load_lds_dwordx4 v5, s[10:11] offset:2048
	global_load_lds_dwordx4 v5, s[10:11] offset:3072
	s_add_u32 s10, s10, 0x4000
	s_addc_u32 s11, s11, 0
	s_add_u32 s41, s41, 0x4000
	s_and_b32 s41, s41, 0x1ffff
	ds_read_b64 v[72:73], v6 offset:2064
	ds_read_b128 v[74:77], v6 offset:2320
	ds_read_b128 v[78:81], v6 offset:2576
	ds_read_u16 v82, v7 offset:2064
	ds_read_b64 v[84:85], v6 offset:3088
	ds_read_b128 v[86:89], v6 offset:3344
	ds_read_b128 v[90:93], v6 offset:3600
	ds_read_u16 v94, v7 offset:3088
	v_fma_mix_f32 v14, v10, v26, 0 op_sel:[0,0,0] op_sel_hi:[0,1,0]
	v_fma_mix_f32 v63, v10, v152, 0 op_sel:[0,0,0] op_sel_hi:[0,1,0]
	v_fma_mix_f32 v14, v11, v26, v14 op_sel:[0,1,0] op_sel_hi:[0,1,0]
	v_fma_mix_f32 v63, v11, v152, v63 op_sel:[0,1,0] op_sel_hi:[0,1,0]
	v_fma_mix_f32 v14, v12, v27, v14 op_sel:[0,0,0] op_sel_hi:[0,1,0]
	v_fma_mix_f32 v63, v12, v153, v63 op_sel:[0,0,0] op_sel_hi:[0,1,0]
	v_fma_mix_f32 v14, v13, v27, v14 op_sel:[0,1,0] op_sel_hi:[0,1,0]
	v_fma_mix_f32 v16, v10, v24, 0 op_sel:[0,0,0] op_sel_hi:[0,1,0]
	v_fma_mix_f32 v17, v11, v24, 0 op_sel:[0,1,0] op_sel_hi:[0,1,0]
	v_add_f32_dpp v20, v14, v14 quad_perm:[1,0,3,2] row_mask:0xf bank_mask:0xf bound_ctrl:1
	v_fma_mix_f32 v63, v13, v153, v63 op_sel:[0,1,0] op_sel_hi:[0,1,0]
	v_fma_mix_f32 v18, v12, v25, 0 op_sel:[0,0,0] op_sel_hi:[0,1,0]
	v_add_f32_dpp v20, v20, v20 quad_perm:[2,3,0,1] row_mask:0xf bank_mask:0xf bound_ctrl:1
	v_fma_mix_f32 v19, v13, v25, 0 op_sel:[0,1,0] op_sel_hi:[0,1,0]
	v_fma_mix_f32 v16, v34, v30, v16 op_sel:[0,0,0] op_sel_hi:[1,1,0]
	v_add_f32_dpp v20, v20, v20 row_half_mirror row_mask:0xf bank_mask:0xf bound_ctrl:1
	v_fma_mix_f32 v17, v34, v30, v17 op_sel:[0,1,0] op_sel_hi:[1,1,0]
	v_fma_mix_f32 v18, v34, v31, v18 op_sel:[0,0,0] op_sel_hi:[1,1,0]
	v_add_f32_dpp v20, v20, v20 row_mirror row_mask:0xf bank_mask:0xf bound_ctrl:1
	v_fma_mix_f32 v19, v34, v31, v19 op_sel:[0,1,0] op_sel_hi:[1,1,0]
	v_fma_mix_f32 v10, v20, v28, v16 op_sel:[0,0,0] op_sel_hi:[0,1,0]
	v_fma_mix_f32 v11, v20, v28, v17 op_sel:[0,1,0] op_sel_hi:[0,1,0]
	v_fma_mix_f32 v12, v20, v29, v18 op_sel:[0,0,0] op_sel_hi:[0,1,0]
	v_fma_mix_f32 v13, v20, v29, v19 op_sel:[0,1,0] op_sel_hi:[0,1,0]
	s_waitcnt lgkmcnt(8)
	s_cmp_eq_u32 s14, 0
	s_cbranch_scc1 .Lrw_skip_d0
	v_add_f32_dpp v48, v48, v48 row_ror:8 row_mask:0xf bank_mask:0x3
	v_add_f32_dpp v49, v49, v49 row_ror:8 row_mask:0xf bank_mask:0x3
	v_add_f32_dpp v50, v50, v50 row_ror:8 row_mask:0xf bank_mask:0x3
	v_add_f32_dpp v51, v51, v51 row_ror:8 row_mask:0xf bank_mask:0x3
	v_add_f32_dpp v52, v52, v52 row_ror:8 row_mask:0xf bank_mask:0x3
	v_add_f32_dpp v53, v53, v53 row_ror:8 row_mask:0xf bank_mask:0x3
	v_add_f32_dpp v54, v54, v54 row_ror:8 row_mask:0xf bank_mask:0x3
	v_add_f32_dpp v55, v55, v55 row_ror:8 row_mask:0xf bank_mask:0x3
	v_add_f32_dpp v48, v56, v56 row_ror:8 row_mask:0xf bank_mask:0xc
	v_add_f32_dpp v49, v57, v57 row_ror:8 row_mask:0xf bank_mask:0xc
	v_add_f32_dpp v50, v58, v58 row_ror:8 row_mask:0xf bank_mask:0xc
	v_add_f32_dpp v51, v59, v59 row_ror:8 row_mask:0xf bank_mask:0xc
	v_add_f32_dpp v52, v60, v60 row_ror:8 row_mask:0xf bank_mask:0xc
	v_add_f32_dpp v53, v61, v61 row_ror:8 row_mask:0xf bank_mask:0xc
	v_add_f32_dpp v54, v62, v62 row_ror:8 row_mask:0xf bank_mask:0xc
	v_add_f32_dpp v55, v63, v63 row_ror:8 row_mask:0xf bank_mask:0xc
	v_add_f32_dpp v48, v48, v48 row_ror:12 row_mask:0xf bank_mask:0x5
	v_add_f32_dpp v49, v49, v49 row_ror:12 row_mask:0xf bank_mask:0x5
	v_add_f32_dpp v50, v50, v50 row_ror:12 row_mask:0xf bank_mask:0x5
	v_add_f32_dpp v51, v51, v51 row_ror:12 row_mask:0xf bank_mask:0x5
	v_add_f32_dpp v48, v52, v52 row_ror:4 row_mask:0xf bank_mask:0xa
	v_add_f32_dpp v49, v53, v53 row_ror:4 row_mask:0xf bank_mask:0xa
	v_add_f32_dpp v50, v54, v54 row_ror:4 row_mask:0xf bank_mask:0xa
	v_add_f32_dpp v51, v55, v55 row_ror:4 row_mask:0xf bank_mask:0xa
	v_add_f32_dpp v64, v48, v48 quad_perm:[2,3,0,1] row_mask:0xf bank_mask:0xf bound_ctrl:1
	v_add_f32_dpp v65, v50, v50 quad_perm:[2,3,0,1] row_mask:0xf bank_mask:0xf bound_ctrl:1
	v_cndmask_b32_e64 v56, v64, v65, s[50:51]
	v_add_f32_dpp v64, v49, v49 quad_perm:[2,3,0,1] row_mask:0xf bank_mask:0xf bound_ctrl:1
	v_add_f32_dpp v65, v51, v51 quad_perm:[2,3,0,1] row_mask:0xf bank_mask:0xf bound_ctrl:1
	v_cndmask_b32_e64 v57, v64, v65, s[50:51]
	v_add_f32_dpp v64, v56, v56 quad_perm:[1,0,3,2] row_mask:0xf bank_mask:0xf bound_ctrl:1
	s_nop 0
	v_add_f32_dpp v65, v57, v57 quad_perm:[1,0,3,2] row_mask:0xf bank_mask:0xf bound_ctrl:1
	v_cndmask_b32_e64 v66, v64, v65, s[48:49]
	v_cvt_pk_bf16_f32 v66, v66, v66
	global_store_short v8, v66, s[12:13]
	s_add_u32 s12, s12, 0x8000
	s_addc_u32 s13, s13, 0
.Lrw_skip_d0:
	v_fma_mix_f32 v14, v10, v38, 0 op_sel:[0,0,0] op_sel_hi:[0,1,0]
	v_fma_mix_f32 v48, v10, v32, 0 op_sel:[0,0,0] op_sel_hi:[0,1,0]
	v_fma_mix_f32 v14, v11, v38, v14 op_sel:[0,1,0] op_sel_hi:[0,1,0]
	v_fma_mix_f32 v48, v11, v32, v48 op_sel:[0,1,0] op_sel_hi:[0,1,0]
	v_fma_mix_f32 v14, v12, v39, v14 op_sel:[0,0,0] op_sel_hi:[0,1,0]
	v_fma_mix_f32 v48, v12, v33, v48 op_sel:[0,0,0] op_sel_hi:[0,1,0]
	v_fma_mix_f32 v14, v13, v39, v14 op_sel:[0,1,0] op_sel_hi:[0,1,0]
	v_fma_mix_f32 v16, v10, v36, 0 op_sel:[0,0,0] op_sel_hi:[0,1,0]
	v_fma_mix_f32 v17, v11, v36, 0 op_sel:[0,1,0] op_sel_hi:[0,1,0]
	v_add_f32_dpp v20, v14, v14 quad_perm:[1,0,3,2] row_mask:0xf bank_mask:0xf bound_ctrl:1
	v_fma_mix_f32 v48, v13, v33, v48 op_sel:[0,1,0] op_sel_hi:[0,1,0]
	v_fma_mix_f32 v18, v12, v37, 0 op_sel:[0,0,0] op_sel_hi:[0,1,0]
	v_add_f32_dpp v20, v20, v20 quad_perm:[2,3,0,1] row_mask:0xf bank_mask:0xf bound_ctrl:1
	v_fma_mix_f32 v19, v13, v37, 0 op_sel:[0,1,0] op_sel_hi:[0,1,0]
	v_fma_mix_f32 v16, v46, v42, v16 op_sel:[0,0,0] op_sel_hi:[1,1,0]
	v_add_f32_dpp v20, v20, v20 row_half_mirror row_mask:0xf bank_mask:0xf bound_ctrl:1
	v_fma_mix_f32 v17, v46, v42, v17 op_sel:[0,1,0] op_sel_hi:[1,1,0]
	v_fma_mix_f32 v18, v46, v43, v18 op_sel:[0,0,0] op_sel_hi:[1,1,0]
	v_add_f32_dpp v20, v20, v20 row_mirror row_mask:0xf bank_mask:0xf bound_ctrl:1
	v_fma_mix_f32 v19, v46, v43, v19 op_sel:[0,1,0] op_sel_hi:[1,1,0]
	v_fma_mix_f32 v10, v20, v40, v16 op_sel:[0,0,0] op_sel_hi:[0,1,0]
	v_fma_mix_f32 v11, v20, v40, v17 op_sel:[0,1,0] op_sel_hi:[0,1,0]
	v_fma_mix_f32 v12, v20, v41, v18 op_sel:[0,0,0] op_sel_hi:[0,1,0]
	v_fma_mix_f32 v13, v20, v41, v19 op_sel:[0,1,0] op_sel_hi:[0,1,0]
	s_waitcnt lgkmcnt(4)
	ds_read_b64 v[108:109], v6 offset:4112
	ds_read_b128 v[110:113], v6 offset:4368
	ds_read_b128 v[114:117], v6 offset:4624
	ds_read_u16 v118, v7 offset:4112
	ds_read_b64 v[120:121], v6 offset:5136
	ds_read_b128 v[122:125], v6 offset:5392
	ds_read_b128 v[126:129], v6 offset:5648
	ds_read_u16 v130, v7 offset:5136
	v_fma_mix_f32 v14, v10, v74, 0 op_sel:[0,0,0] op_sel_hi:[0,1,0]
	v_fma_mix_f32 v49, v10, v44, 0 op_sel:[0,0,0] op_sel_hi:[0,1,0]
	v_fma_mix_f32 v14, v11, v74, v14 op_sel:[0,1,0] op_sel_hi:[0,1,0]
	v_fma_mix_f32 v49, v11, v44, v49 op_sel:[0,1,0] op_sel_hi:[0,1,0]
	v_fma_mix_f32 v14, v12, v75, v14 op_sel:[0,0,0] op_sel_hi:[0,1,0]
	v_fma_mix_f32 v49, v12, v45, v49 op_sel:[0,0,0] op_sel_hi:[0,1,0]
	v_fma_mix_f32 v14, v13, v75, v14 op_sel:[0,1,0] op_sel_hi:[0,1,0]
	v_fma_mix_f32 v16, v10, v72, 0 op_sel:[0,0,0] op_sel_hi:[0,1,0]
	v_fma_mix_f32 v17, v11, v72, 0 op_sel:[0,1,0] op_sel_hi:[0,1,0]
	v_add_f32_dpp v20, v14, v14 quad_perm:[1,0,3,2] row_mask:0xf bank_mask:0xf bound_ctrl:1
	v_fma_mix_f32 v49, v13, v45, v49 op_sel:[0,1,0] op_sel_hi:[0,1,0]
	v_fma_mix_f32 v18, v12, v73, 0 op_sel:[0,0,0] op_sel_hi:[0,1,0]
	v_add_f32_dpp v20, v20, v20 quad_perm:[2,3,0,1] row_mask:0xf bank_mask:0xf bound_ctrl:1
	v_fma_mix_f32 v19, v13, v73, 0 op_sel:[0,1,0] op_sel_hi:[0,1,0]
	v_fma_mix_f32 v16, v82, v78, v16 op_sel:[0,0,0] op_sel_hi:[1,1,0]
	v_add_f32_dpp v20, v20, v20 row_half_mirror row_mask:0xf bank_mask:0xf bound_ctrl:1
	v_fma_mix_f32 v17, v82, v78, v17 op_sel:[0,1,0] op_sel_hi:[1,1,0]
	v_fma_mix_f32 v18, v82, v79, v18 op_sel:[0,0,0] op_sel_hi:[1,1,0]
	v_add_f32_dpp v20, v20, v20 row_mirror row_mask:0xf bank_mask:0xf bound_ctrl:1
	v_fma_mix_f32 v19, v82, v79, v19 op_sel:[0,1,0] op_sel_hi:[1,1,0]
	v_fma_mix_f32 v10, v20, v76, v16 op_sel:[0,0,0] op_sel_hi:[0,1,0]
	v_fma_mix_f32 v11, v20, v76, v17 op_sel:[0,1,0] op_sel_hi:[0,1,0]
	v_fma_mix_f32 v12, v20, v77, v18 op_sel:[0,0,0] op_sel_hi:[0,1,0]
	v_fma_mix_f32 v13, v20, v77, v19 op_sel:[0,1,0] op_sel_hi:[0,1,0]
	s_waitcnt lgkmcnt(8)
	v_fma_mix_f32 v14, v10, v86, 0 op_sel:[0,0,0] op_sel_hi:[0,1,0]
	v_fma_mix_f32 v50, v10, v80, 0 op_sel:[0,0,0] op_sel_hi:[0,1,0]
	v_fma_mix_f32 v14, v11, v86, v14 op_sel:[0,1,0] op_sel_hi:[0,1,0]
	v_fma_mix_f32 v50, v11, v80, v50 op_sel:[0,1,0] op_sel_hi:[0,1,0]
	v_fma_mix_f32 v14, v12, v87, v14 op_sel:[0,0,0] op_sel_hi:[0,1,0]
	v_fma_mix_f32 v50, v12, v81, v50 op_sel:[0,0,0] op_sel_hi:[0,1,0]
	v_fma_mix_f32 v14, v13, v87, v14 op_sel:[0,1,0] op_sel_hi:[0,1,0]
	v_fma_mix_f32 v16, v10, v84, 0 op_sel:[0,0,0] op_sel_hi:[0,1,0]
	v_fma_mix_f32 v17, v11, v84, 0 op_sel:[0,1,0] op_sel_hi:[0,1,0]
	v_add_f32_dpp v20, v14, v14 quad_perm:[1,0,3,2] row_mask:0xf bank_mask:0xf bound_ctrl:1
	v_fma_mix_f32 v50, v13, v81, v50 op_sel:[0,1,0] op_sel_hi:[0,1,0]
	v_fma_mix_f32 v18, v12, v85, 0 op_sel:[0,0,0] op_sel_hi:[0,1,0]
	v_add_f32_dpp v20, v20, v20 quad_perm:[2,3,0,1] row_mask:0xf bank_mask:0xf bound_ctrl:1
	v_fma_mix_f32 v19, v13, v85, 0 op_sel:[0,1,0] op_sel_hi:[0,1,0]
	v_fma_mix_f32 v16, v94, v90, v16 op_sel:[0,0,0] op_sel_hi:[1,1,0]
	v_add_f32_dpp v20, v20, v20 row_half_mirror row_mask:0xf bank_mask:0xf bound_ctrl:1
	v_fma_mix_f32 v17, v94, v90, v17 op_sel:[0,1,0] op_sel_hi:[1,1,0]
	v_fma_mix_f32 v18, v94, v91, v18 op_sel:[0,0,0] op_sel_hi:[1,1,0]
	v_add_f32_dpp v20, v20, v20 row_mirror row_mask:0xf bank_mask:0xf bound_ctrl:1
	v_fma_mix_f32 v19, v94, v91, v19 op_sel:[0,1,0] op_sel_hi:[1,1,0]
	v_fma_mix_f32 v10, v20, v88, v16 op_sel:[0,0,0] op_sel_hi:[0,1,0]
	v_fma_mix_f32 v11, v20, v88, v17 op_sel:[0,1,0] op_sel_hi:[0,1,0]
	v_fma_mix_f32 v12, v20, v89, v18 op_sel:[0,0,0] op_sel_hi:[0,1,0]
	v_fma_mix_f32 v13, v20, v89, v19 op_sel:[0,1,0] op_sel_hi:[0,1,0]
	s_waitcnt lgkmcnt(4)
	ds_read_b64 v[132:133], v6 offset:6160
	ds_read_b128 v[134:137], v6 offset:6416
	ds_read_b128 v[138:141], v6 offset:6672
	ds_read_u16 v142, v7 offset:6160
	ds_read_b64 v[144:145], v6 offset:7184
	ds_read_b128 v[146:149], v6 offset:7440
	ds_read_b128 v[150:153], v6 offset:7696
	ds_read_u16 v154, v7 offset:7184
	v_fma_mix_f32 v14, v10, v110, 0 op_sel:[0,0,0] op_sel_hi:[0,1,0]
	v_fma_mix_f32 v51, v10, v92, 0 op_sel:[0,0,0] op_sel_hi:[0,1,0]
	v_fma_mix_f32 v14, v11, v110, v14 op_sel:[0,1,0] op_sel_hi:[0,1,0]
	v_fma_mix_f32 v51, v11, v92, v51 op_sel:[0,1,0] op_sel_hi:[0,1,0]
	v_fma_mix_f32 v14, v12, v111, v14 op_sel:[0,0,0] op_sel_hi:[0,1,0]
	v_fma_mix_f32 v51, v12, v93, v51 op_sel:[0,0,0] op_sel_hi:[0,1,0]
	v_fma_mix_f32 v14, v13, v111, v14 op_sel:[0,1,0] op_sel_hi:[0,1,0]
	v_fma_mix_f32 v16, v10, v108, 0 op_sel:[0,0,0] op_sel_hi:[0,1,0]
	v_fma_mix_f32 v17, v11, v108, 0 op_sel:[0,1,0] op_sel_hi:[0,1,0]
	v_add_f32_dpp v20, v14, v14 quad_perm:[1,0,3,2] row_mask:0xf bank_mask:0xf bound_ctrl:1
	v_fma_mix_f32 v51, v13, v93, v51 op_sel:[0,1,0] op_sel_hi:[0,1,0]
	v_fma_mix_f32 v18, v12, v109, 0 op_sel:[0,0,0] op_sel_hi:[0,1,0]
	v_add_f32_dpp v20, v20, v20 quad_perm:[2,3,0,1] row_mask:0xf bank_mask:0xf bound_ctrl:1
	v_fma_mix_f32 v19, v13, v109, 0 op_sel:[0,1,0] op_sel_hi:[0,1,0]
	v_fma_mix_f32 v16, v118, v114, v16 op_sel:[0,0,0] op_sel_hi:[1,1,0]
	v_add_f32_dpp v20, v20, v20 row_half_mirror row_mask:0xf bank_mask:0xf bound_ctrl:1
	v_fma_mix_f32 v17, v118, v114, v17 op_sel:[0,1,0] op_sel_hi:[1,1,0]
	v_fma_mix_f32 v18, v118, v115, v18 op_sel:[0,0,0] op_sel_hi:[1,1,0]
	v_add_f32_dpp v20, v20, v20 row_mirror row_mask:0xf bank_mask:0xf bound_ctrl:1
	v_fma_mix_f32 v19, v118, v115, v19 op_sel:[0,1,0] op_sel_hi:[1,1,0]
	v_fma_mix_f32 v10, v20, v112, v16 op_sel:[0,0,0] op_sel_hi:[0,1,0]
	v_fma_mix_f32 v11, v20, v112, v17 op_sel:[0,1,0] op_sel_hi:[0,1,0]
	v_fma_mix_f32 v12, v20, v113, v18 op_sel:[0,0,0] op_sel_hi:[0,1,0]
	v_fma_mix_f32 v13, v20, v113, v19 op_sel:[0,1,0] op_sel_hi:[0,1,0]
	s_waitcnt lgkmcnt(8)
	v_fma_mix_f32 v14, v10, v122, 0 op_sel:[0,0,0] op_sel_hi:[0,1,0]
	v_fma_mix_f32 v52, v10, v116, 0 op_sel:[0,0,0] op_sel_hi:[0,1,0]
	v_fma_mix_f32 v14, v11, v122, v14 op_sel:[0,1,0] op_sel_hi:[0,1,0]
	v_fma_mix_f32 v52, v11, v116, v52 op_sel:[0,1,0] op_sel_hi:[0,1,0]
	v_fma_mix_f32 v14, v12, v123, v14 op_sel:[0,0,0] op_sel_hi:[0,1,0]
	v_fma_mix_f32 v52, v12, v117, v52 op_sel:[0,0,0] op_sel_hi:[0,1,0]
	v_fma_mix_f32 v14, v13, v123, v14 op_sel:[0,1,0] op_sel_hi:[0,1,0]
	v_fma_mix_f32 v16, v10, v120, 0 op_sel:[0,0,0] op_sel_hi:[0,1,0]
	v_fma_mix_f32 v17, v11, v120, 0 op_sel:[0,1,0] op_sel_hi:[0,1,0]
	v_add_f32_dpp v20, v14, v14 quad_perm:[1,0,3,2] row_mask:0xf bank_mask:0xf bound_ctrl:1
	v_fma_mix_f32 v52, v13, v117, v52 op_sel:[0,1,0] op_sel_hi:[0,1,0]
	v_fma_mix_f32 v18, v12, v121, 0 op_sel:[0,0,0] op_sel_hi:[0,1,0]
	v_add_f32_dpp v20, v20, v20 quad_perm:[2,3,0,1] row_mask:0xf bank_mask:0xf bound_ctrl:1
	v_fma_mix_f32 v19, v13, v121, 0 op_sel:[0,1,0] op_sel_hi:[0,1,0]
	v_fma_mix_f32 v16, v130, v126, v16 op_sel:[0,0,0] op_sel_hi:[1,1,0]
	v_add_f32_dpp v20, v20, v20 row_half_mirror row_mask:0xf bank_mask:0xf bound_ctrl:1
	v_fma_mix_f32 v17, v130, v126, v17 op_sel:[0,1,0] op_sel_hi:[1,1,0]
	v_fma_mix_f32 v18, v130, v127, v18 op_sel:[0,0,0] op_sel_hi:[1,1,0]
	v_add_f32_dpp v20, v20, v20 row_mirror row_mask:0xf bank_mask:0xf bound_ctrl:1
	v_fma_mix_f32 v19, v130, v127, v19 op_sel:[0,1,0] op_sel_hi:[1,1,0]
	v_fma_mix_f32 v10, v20, v124, v16 op_sel:[0,0,0] op_sel_hi:[0,1,0]
	v_fma_mix_f32 v11, v20, v124, v17 op_sel:[0,1,0] op_sel_hi:[0,1,0]
	v_fma_mix_f32 v12, v20, v125, v18 op_sel:[0,0,0] op_sel_hi:[0,1,0]
	v_fma_mix_f32 v13, v20, v125, v19 op_sel:[0,1,0] op_sel_hi:[0,1,0]
	s_waitcnt lgkmcnt(4)
	ds_read_b64 v[24:25], v6 offset:8208
	ds_read_b128 v[26:29], v6 offset:8464
	ds_read_b128 v[30:33], v6 offset:8720
	ds_read_u16 v34, v7 offset:8208
	ds_read_b64 v[36:37], v6 offset:9232
	ds_read_b128 v[38:41], v6 offset:9488
	ds_read_b128 v[42:45], v6 offset:9744
	ds_read_u16 v46, v7 offset:9232
	v_fma_mix_f32 v14, v10, v134, 0 op_sel:[0,0,0] op_sel_hi:[0,1,0]
	v_fma_mix_f32 v53, v10, v128, 0 op_sel:[0,0,0] op_sel_hi:[0,1,0]
	v_fma_mix_f32 v14, v11, v134, v14 op_sel:[0,1,0] op_sel_hi:[0,1,0]
	v_fma_mix_f32 v53, v11, v128, v53 op_sel:[0,1,0] op_sel_hi:[0,1,0]
	v_fma_mix_f32 v14, v12, v135, v14 op_sel:[0,0,0] op_sel_hi:[0,1,0]
	v_fma_mix_f32 v53, v12, v129, v53 op_sel:[0,0,0] op_sel_hi:[0,1,0]
	v_fma_mix_f32 v14, v13, v135, v14 op_sel:[0,1,0] op_sel_hi:[0,1,0]
	v_fma_mix_f32 v16, v10, v132, 0 op_sel:[0,0,0] op_sel_hi:[0,1,0]
	v_fma_mix_f32 v17, v11, v132, 0 op_sel:[0,1,0] op_sel_hi:[0,1,0]
	v_add_f32_dpp v20, v14, v14 quad_perm:[1,0,3,2] row_mask:0xf bank_mask:0xf bound_ctrl:1
	v_fma_mix_f32 v53, v13, v129, v53 op_sel:[0,1,0] op_sel_hi:[0,1,0]
	v_fma_mix_f32 v18, v12, v133, 0 op_sel:[0,0,0] op_sel_hi:[0,1,0]
	v_add_f32_dpp v20, v20, v20 quad_perm:[2,3,0,1] row_mask:0xf bank_mask:0xf bound_ctrl:1
	v_fma_mix_f32 v19, v13, v133, 0 op_sel:[0,1,0] op_sel_hi:[0,1,0]
	v_fma_mix_f32 v16, v142, v138, v16 op_sel:[0,0,0] op_sel_hi:[1,1,0]
	v_add_f32_dpp v20, v20, v20 row_half_mirror row_mask:0xf bank_mask:0xf bound_ctrl:1
	v_fma_mix_f32 v17, v142, v138, v17 op_sel:[0,1,0] op_sel_hi:[1,1,0]
	v_fma_mix_f32 v18, v142, v139, v18 op_sel:[0,0,0] op_sel_hi:[1,1,0]
	v_add_f32_dpp v20, v20, v20 row_mirror row_mask:0xf bank_mask:0xf bound_ctrl:1
	v_fma_mix_f32 v19, v142, v139, v19 op_sel:[0,1,0] op_sel_hi:[1,1,0]
	v_fma_mix_f32 v10, v20, v136, v16 op_sel:[0,0,0] op_sel_hi:[0,1,0]
	v_fma_mix_f32 v11, v20, v136, v17 op_sel:[0,1,0] op_sel_hi:[0,1,0]
	v_fma_mix_f32 v12, v20, v137, v18 op_sel:[0,0,0] op_sel_hi:[0,1,0]
	v_fma_mix_f32 v13, v20, v137, v19 op_sel:[0,1,0] op_sel_hi:[0,1,0]
	s_waitcnt lgkmcnt(8)
	v_fma_mix_f32 v14, v10, v146, 0 op_sel:[0,0,0] op_sel_hi:[0,1,0]
	v_fma_mix_f32 v54, v10, v140, 0 op_sel:[0,0,0] op_sel_hi:[0,1,0]
	v_fma_mix_f32 v14, v11, v146, v14 op_sel:[0,1,0] op_sel_hi:[0,1,0]
	v_fma_mix_f32 v54, v11, v140, v54 op_sel:[0,1,0] op_sel_hi:[0,1,0]
	v_fma_mix_f32 v14, v12, v147, v14 op_sel:[0,0,0] op_sel_hi:[0,1,0]
	v_fma_mix_f32 v54, v12, v141, v54 op_sel:[0,0,0] op_sel_hi:[0,1,0]
	v_fma_mix_f32 v14, v13, v147, v14 op_sel:[0,1,0] op_sel_hi:[0,1,0]
	v_fma_mix_f32 v16, v10, v144, 0 op_sel:[0,0,0] op_sel_hi:[0,1,0]
	v_fma_mix_f32 v17, v11, v144, 0 op_sel:[0,1,0] op_sel_hi:[0,1,0]
	v_add_f32_dpp v20, v14, v14 quad_perm:[1,0,3,2] row_mask:0xf bank_mask:0xf bound_ctrl:1
	v_fma_mix_f32 v54, v13, v141, v54 op_sel:[0,1,0] op_sel_hi:[0,1,0]
	v_fma_mix_f32 v18, v12, v145, 0 op_sel:[0,0,0] op_sel_hi:[0,1,0]
	v_add_f32_dpp v20, v20, v20 quad_perm:[2,3,0,1] row_mask:0xf bank_mask:0xf bound_ctrl:1
	v_fma_mix_f32 v19, v13, v145, 0 op_sel:[0,1,0] op_sel_hi:[0,1,0]
	v_fma_mix_f32 v16, v154, v150, v16 op_sel:[0,0,0] op_sel_hi:[1,1,0]
	v_add_f32_dpp v20, v20, v20 row_half_mirror row_mask:0xf bank_mask:0xf bound_ctrl:1
	v_fma_mix_f32 v17, v154, v150, v17 op_sel:[0,1,0] op_sel_hi:[1,1,0]
	v_fma_mix_f32 v18, v154, v151, v18 op_sel:[0,0,0] op_sel_hi:[1,1,0]
	v_add_f32_dpp v20, v20, v20 row_mirror row_mask:0xf bank_mask:0xf bound_ctrl:1
	v_fma_mix_f32 v19, v154, v151, v19 op_sel:[0,1,0] op_sel_hi:[1,1,0]
	v_fma_mix_f32 v10, v20, v148, v16 op_sel:[0,0,0] op_sel_hi:[0,1,0]
	v_fma_mix_f32 v11, v20, v148, v17 op_sel:[0,1,0] op_sel_hi:[0,1,0]
	v_fma_mix_f32 v12, v20, v149, v18 op_sel:[0,0,0] op_sel_hi:[0,1,0]
	v_fma_mix_f32 v13, v20, v149, v19 op_sel:[0,1,0] op_sel_hi:[0,1,0]
	s_waitcnt lgkmcnt(4)
	ds_read_b64 v[72:73], v6 offset:10256
	ds_read_b128 v[74:77], v6 offset:10512
	ds_read_b128 v[78:81], v6 offset:10768
	ds_read_u16 v82, v7 offset:10256
	ds_read_b64 v[84:85], v6 offset:11280
	ds_read_b128 v[86:89], v6 offset:11536
	ds_read_b128 v[90:93], v6 offset:11792
	ds_read_u16 v94, v7 offset:11280
	v_fma_mix_f32 v14, v10, v26, 0 op_sel:[0,0,0] op_sel_hi:[0,1,0]
	v_fma_mix_f32 v55, v10, v152, 0 op_sel:[0,0,0] op_sel_hi:[0,1,0]
	v_fma_mix_f32 v14, v11, v26, v14 op_sel:[0,1,0] op_sel_hi:[0,1,0]
	v_fma_mix_f32 v55, v11, v152, v55 op_sel:[0,1,0] op_sel_hi:[0,1,0]
	v_fma_mix_f32 v14, v12, v27, v14 op_sel:[0,0,0] op_sel_hi:[0,1,0]
	v_fma_mix_f32 v55, v12, v153, v55 op_sel:[0,0,0] op_sel_hi:[0,1,0]
	v_fma_mix_f32 v14, v13, v27, v14 op_sel:[0,1,0] op_sel_hi:[0,1,0]
	v_fma_mix_f32 v16, v10, v24, 0 op_sel:[0,0,0] op_sel_hi:[0,1,0]
	v_fma_mix_f32 v17, v11, v24, 0 op_sel:[0,1,0] op_sel_hi:[0,1,0]
	v_add_f32_dpp v20, v14, v14 quad_perm:[1,0,3,2] row_mask:0xf bank_mask:0xf bound_ctrl:1
	v_fma_mix_f32 v55, v13, v153, v55 op_sel:[0,1,0] op_sel_hi:[0,1,0]
	v_fma_mix_f32 v18, v12, v25, 0 op_sel:[0,0,0] op_sel_hi:[0,1,0]
	v_add_f32_dpp v20, v20, v20 quad_perm:[2,3,0,1] row_mask:0xf bank_mask:0xf bound_ctrl:1
	v_fma_mix_f32 v19, v13, v25, 0 op_sel:[0,1,0] op_sel_hi:[0,1,0]
	v_fma_mix_f32 v16, v34, v30, v16 op_sel:[0,0,0] op_sel_hi:[1,1,0]
	v_add_f32_dpp v20, v20, v20 row_half_mirror row_mask:0xf bank_mask:0xf bound_ctrl:1
	v_fma_mix_f32 v17, v34, v30, v17 op_sel:[0,1,0] op_sel_hi:[1,1,0]
	v_fma_mix_f32 v18, v34, v31, v18 op_sel:[0,0,0] op_sel_hi:[1,1,0]
	v_add_f32_dpp v20, v20, v20 row_mirror row_mask:0xf bank_mask:0xf bound_ctrl:1
	v_fma_mix_f32 v19, v34, v31, v19 op_sel:[0,1,0] op_sel_hi:[1,1,0]
	v_fma_mix_f32 v10, v20, v28, v16 op_sel:[0,0,0] op_sel_hi:[0,1,0]
	v_fma_mix_f32 v11, v20, v28, v17 op_sel:[0,1,0] op_sel_hi:[0,1,0]
	v_fma_mix_f32 v12, v20, v29, v18 op_sel:[0,0,0] op_sel_hi:[0,1,0]
	v_fma_mix_f32 v13, v20, v29, v19 op_sel:[0,1,0] op_sel_hi:[0,1,0]
	s_waitcnt lgkmcnt(8)
	v_fma_mix_f32 v14, v10, v38, 0 op_sel:[0,0,0] op_sel_hi:[0,1,0]
	v_fma_mix_f32 v56, v10, v32, 0 op_sel:[0,0,0] op_sel_hi:[0,1,0]
	v_fma_mix_f32 v14, v11, v38, v14 op_sel:[0,1,0] op_sel_hi:[0,1,0]
	v_fma_mix_f32 v56, v11, v32, v56 op_sel:[0,1,0] op_sel_hi:[0,1,0]
	v_fma_mix_f32 v14, v12, v39, v14 op_sel:[0,0,0] op_sel_hi:[0,1,0]
	v_fma_mix_f32 v56, v12, v33, v56 op_sel:[0,0,0] op_sel_hi:[0,1,0]
	v_fma_mix_f32 v14, v13, v39, v14 op_sel:[0,1,0] op_sel_hi:[0,1,0]
	v_fma_mix_f32 v16, v10, v36, 0 op_sel:[0,0,0] op_sel_hi:[0,1,0]
	v_fma_mix_f32 v17, v11, v36, 0 op_sel:[0,1,0] op_sel_hi:[0,1,0]
	v_add_f32_dpp v20, v14, v14 quad_perm:[1,0,3,2] row_mask:0xf bank_mask:0xf bound_ctrl:1
	v_fma_mix_f32 v56, v13, v33, v56 op_sel:[0,1,0] op_sel_hi:[0,1,0]
	v_fma_mix_f32 v18, v12, v37, 0 op_sel:[0,0,0] op_sel_hi:[0,1,0]
	v_add_f32_dpp v20, v20, v20 quad_perm:[2,3,0,1] row_mask:0xf bank_mask:0xf bound_ctrl:1
	v_fma_mix_f32 v19, v13, v37, 0 op_sel:[0,1,0] op_sel_hi:[0,1,0]
	v_fma_mix_f32 v16, v46, v42, v16 op_sel:[0,0,0] op_sel_hi:[1,1,0]
	v_add_f32_dpp v20, v20, v20 row_half_mirror row_mask:0xf bank_mask:0xf bound_ctrl:1
	v_fma_mix_f32 v17, v46, v42, v17 op_sel:[0,1,0] op_sel_hi:[1,1,0]
	v_fma_mix_f32 v18, v46, v43, v18 op_sel:[0,0,0] op_sel_hi:[1,1,0]
	v_add_f32_dpp v20, v20, v20 row_mirror row_mask:0xf bank_mask:0xf bound_ctrl:1
	v_fma_mix_f32 v19, v46, v43, v19 op_sel:[0,1,0] op_sel_hi:[1,1,0]
	v_fma_mix_f32 v10, v20, v40, v16 op_sel:[0,0,0] op_sel_hi:[0,1,0]
	v_fma_mix_f32 v11, v20, v40, v17 op_sel:[0,1,0] op_sel_hi:[0,1,0]
	v_fma_mix_f32 v12, v20, v41, v18 op_sel:[0,0,0] op_sel_hi:[0,1,0]
	v_fma_mix_f32 v13, v20, v41, v19 op_sel:[0,1,0] op_sel_hi:[0,1,0]
	s_waitcnt lgkmcnt(4)
	ds_read_b64 v[108:109], v6 offset:12304
	ds_read_b128 v[110:113], v6 offset:12560
	ds_read_b128 v[114:117], v6 offset:12816
	ds_read_u16 v118, v7 offset:12304
	ds_read_b64 v[120:121], v6 offset:13328
	ds_read_b128 v[122:125], v6 offset:13584
	ds_read_b128 v[126:129], v6 offset:13840
	ds_read_u16 v130, v7 offset:13328
	v_fma_mix_f32 v14, v10, v74, 0 op_sel:[0,0,0] op_sel_hi:[0,1,0]
	v_fma_mix_f32 v57, v10, v44, 0 op_sel:[0,0,0] op_sel_hi:[0,1,0]
	v_fma_mix_f32 v14, v11, v74, v14 op_sel:[0,1,0] op_sel_hi:[0,1,0]
	v_fma_mix_f32 v57, v11, v44, v57 op_sel:[0,1,0] op_sel_hi:[0,1,0]
	v_fma_mix_f32 v14, v12, v75, v14 op_sel:[0,0,0] op_sel_hi:[0,1,0]
	v_fma_mix_f32 v57, v12, v45, v57 op_sel:[0,0,0] op_sel_hi:[0,1,0]
	v_fma_mix_f32 v14, v13, v75, v14 op_sel:[0,1,0] op_sel_hi:[0,1,0]
	v_fma_mix_f32 v16, v10, v72, 0 op_sel:[0,0,0] op_sel_hi:[0,1,0]
	v_fma_mix_f32 v17, v11, v72, 0 op_sel:[0,1,0] op_sel_hi:[0,1,0]
	v_add_f32_dpp v20, v14, v14 quad_perm:[1,0,3,2] row_mask:0xf bank_mask:0xf bound_ctrl:1
	v_fma_mix_f32 v57, v13, v45, v57 op_sel:[0,1,0] op_sel_hi:[0,1,0]
	v_fma_mix_f32 v18, v12, v73, 0 op_sel:[0,0,0] op_sel_hi:[0,1,0]
	v_add_f32_dpp v20, v20, v20 quad_perm:[2,3,0,1] row_mask:0xf bank_mask:0xf bound_ctrl:1
	v_fma_mix_f32 v19, v13, v73, 0 op_sel:[0,1,0] op_sel_hi:[0,1,0]
	v_fma_mix_f32 v16, v82, v78, v16 op_sel:[0,0,0] op_sel_hi:[1,1,0]
	v_add_f32_dpp v20, v20, v20 row_half_mirror row_mask:0xf bank_mask:0xf bound_ctrl:1
	v_fma_mix_f32 v17, v82, v78, v17 op_sel:[0,1,0] op_sel_hi:[1,1,0]
	v_fma_mix_f32 v18, v82, v79, v18 op_sel:[0,0,0] op_sel_hi:[1,1,0]
	v_add_f32_dpp v20, v20, v20 row_mirror row_mask:0xf bank_mask:0xf bound_ctrl:1
	v_fma_mix_f32 v19, v82, v79, v19 op_sel:[0,1,0] op_sel_hi:[1,1,0]
	v_fma_mix_f32 v10, v20, v76, v16 op_sel:[0,0,0] op_sel_hi:[0,1,0]
	v_fma_mix_f32 v11, v20, v76, v17 op_sel:[0,1,0] op_sel_hi:[0,1,0]
	v_fma_mix_f32 v12, v20, v77, v18 op_sel:[0,0,0] op_sel_hi:[0,1,0]
	v_fma_mix_f32 v13, v20, v77, v19 op_sel:[0,1,0] op_sel_hi:[0,1,0]
	s_waitcnt lgkmcnt(8)
	v_fma_mix_f32 v14, v10, v86, 0 op_sel:[0,0,0] op_sel_hi:[0,1,0]
	v_fma_mix_f32 v58, v10, v80, 0 op_sel:[0,0,0] op_sel_hi:[0,1,0]
	v_fma_mix_f32 v14, v11, v86, v14 op_sel:[0,1,0] op_sel_hi:[0,1,0]
	v_fma_mix_f32 v58, v11, v80, v58 op_sel:[0,1,0] op_sel_hi:[0,1,0]
	v_fma_mix_f32 v14, v12, v87, v14 op_sel:[0,0,0] op_sel_hi:[0,1,0]
	v_fma_mix_f32 v58, v12, v81, v58 op_sel:[0,0,0] op_sel_hi:[0,1,0]
	v_fma_mix_f32 v14, v13, v87, v14 op_sel:[0,1,0] op_sel_hi:[0,1,0]
	v_fma_mix_f32 v16, v10, v84, 0 op_sel:[0,0,0] op_sel_hi:[0,1,0]
	v_fma_mix_f32 v17, v11, v84, 0 op_sel:[0,1,0] op_sel_hi:[0,1,0]
	v_add_f32_dpp v20, v14, v14 quad_perm:[1,0,3,2] row_mask:0xf bank_mask:0xf bound_ctrl:1
	v_fma_mix_f32 v58, v13, v81, v58 op_sel:[0,1,0] op_sel_hi:[0,1,0]
	v_fma_mix_f32 v18, v12, v85, 0 op_sel:[0,0,0] op_sel_hi:[0,1,0]
	v_add_f32_dpp v20, v20, v20 quad_perm:[2,3,0,1] row_mask:0xf bank_mask:0xf bound_ctrl:1
	v_fma_mix_f32 v19, v13, v85, 0 op_sel:[0,1,0] op_sel_hi:[0,1,0]
	v_fma_mix_f32 v16, v94, v90, v16 op_sel:[0,0,0] op_sel_hi:[1,1,0]
	v_add_f32_dpp v20, v20, v20 row_half_mirror row_mask:0xf bank_mask:0xf bound_ctrl:1
	v_fma_mix_f32 v17, v94, v90, v17 op_sel:[0,1,0] op_sel_hi:[1,1,0]
	v_fma_mix_f32 v18, v94, v91, v18 op_sel:[0,0,0] op_sel_hi:[1,1,0]
	v_add_f32_dpp v20, v20, v20 row_mirror row_mask:0xf bank_mask:0xf bound_ctrl:1
	v_fma_mix_f32 v19, v94, v91, v19 op_sel:[0,1,0] op_sel_hi:[1,1,0]
	v_fma_mix_f32 v10, v20, v88, v16 op_sel:[0,0,0] op_sel_hi:[0,1,0]
	v_fma_mix_f32 v11, v20, v88, v17 op_sel:[0,1,0] op_sel_hi:[0,1,0]
	v_fma_mix_f32 v12, v20, v89, v18 op_sel:[0,0,0] op_sel_hi:[0,1,0]
	v_fma_mix_f32 v13, v20, v89, v19 op_sel:[0,1,0] op_sel_hi:[0,1,0]
	s_waitcnt lgkmcnt(4)
	ds_read_b64 v[132:133], v6 offset:14352
	ds_read_b128 v[134:137], v6 offset:14608
	ds_read_b128 v[138:141], v6 offset:14864
	ds_read_u16 v142, v7 offset:14352
	ds_read_b64 v[144:145], v6 offset:15376
	ds_read_b128 v[146:149], v6 offset:15632
	ds_read_b128 v[150:153], v6 offset:15888
	ds_read_u16 v154, v7 offset:15376
	v_fma_mix_f32 v14, v10, v110, 0 op_sel:[0,0,0] op_sel_hi:[0,1,0]
	v_fma_mix_f32 v59, v10, v92, 0 op_sel:[0,0,0] op_sel_hi:[0,1,0]
	v_fma_mix_f32 v14, v11, v110, v14 op_sel:[0,1,0] op_sel_hi:[0,1,0]
	v_fma_mix_f32 v59, v11, v92, v59 op_sel:[0,1,0] op_sel_hi:[0,1,0]
	v_fma_mix_f32 v14, v12, v111, v14 op_sel:[0,0,0] op_sel_hi:[0,1,0]
	v_fma_mix_f32 v59, v12, v93, v59 op_sel:[0,0,0] op_sel_hi:[0,1,0]
	v_fma_mix_f32 v14, v13, v111, v14 op_sel:[0,1,0] op_sel_hi:[0,1,0]
	v_fma_mix_f32 v16, v10, v108, 0 op_sel:[0,0,0] op_sel_hi:[0,1,0]
	v_fma_mix_f32 v17, v11, v108, 0 op_sel:[0,1,0] op_sel_hi:[0,1,0]
	v_add_f32_dpp v20, v14, v14 quad_perm:[1,0,3,2] row_mask:0xf bank_mask:0xf bound_ctrl:1
	v_fma_mix_f32 v59, v13, v93, v59 op_sel:[0,1,0] op_sel_hi:[0,1,0]
	v_fma_mix_f32 v18, v12, v109, 0 op_sel:[0,0,0] op_sel_hi:[0,1,0]
	v_add_f32_dpp v20, v20, v20 quad_perm:[2,3,0,1] row_mask:0xf bank_mask:0xf bound_ctrl:1
	v_fma_mix_f32 v19, v13, v109, 0 op_sel:[0,1,0] op_sel_hi:[0,1,0]
	v_fma_mix_f32 v16, v118, v114, v16 op_sel:[0,0,0] op_sel_hi:[1,1,0]
	v_add_f32_dpp v20, v20, v20 row_half_mirror row_mask:0xf bank_mask:0xf bound_ctrl:1
	v_fma_mix_f32 v17, v118, v114, v17 op_sel:[0,1,0] op_sel_hi:[1,1,0]
	v_fma_mix_f32 v18, v118, v115, v18 op_sel:[0,0,0] op_sel_hi:[1,1,0]
	v_add_f32_dpp v20, v20, v20 row_mirror row_mask:0xf bank_mask:0xf bound_ctrl:1
	v_fma_mix_f32 v19, v118, v115, v19 op_sel:[0,1,0] op_sel_hi:[1,1,0]
	v_fma_mix_f32 v10, v20, v112, v16 op_sel:[0,0,0] op_sel_hi:[0,1,0]
	v_fma_mix_f32 v11, v20, v112, v17 op_sel:[0,1,0] op_sel_hi:[0,1,0]
	v_fma_mix_f32 v12, v20, v113, v18 op_sel:[0,0,0] op_sel_hi:[0,1,0]
	v_fma_mix_f32 v13, v20, v113, v19 op_sel:[0,1,0] op_sel_hi:[0,1,0]
	s_waitcnt lgkmcnt(8)
; DEVINL u16 f2bf(float a) { return (u16)(pk2(a, 0.f) & 0xffffu); }
; #define RW_STEP2(B) RW_STEP(B, WvA, XA, KrA, vhA, WvB, XB, KrB, vhB); RW_STEP((B) + 1, WvB, XB, KrB, vhB, WvA, XA, KrA, vhA)
; #define RW_STEP4(B) RW_STEP2(B); RW_STEP2((B) + 2)
; template <int DIR>
; DEVINL void rwkv_scan_dir(const Params& p, int task, int lane, int wave) {
;     ...
;   for (int st = 0; st < 4096; st += 32) {
;     RW_STEP(0, WvA, XA, KrA, vhA, WvB, XB, KrB, vhB);
;     if (st > 0) { const int q0 = st - 16 + seg; yo[(long)(DIR ? (4095 - q0) : q0) * 1024] = f2bf(ykeep); }
;     RW_STEP(1, WvB, XB, KrB, vhB, WvA, XA, KrA, vhA);
;     RW_STEP2(2); RW_STEP4(4); RW_STEP4(8); RW_STEP4(12);
;     RW_STEP(16, WvA, XA, KrA, vhA, WvB, XB, KrB, vhB);
;     { const int q0 = st + seg; yo[(long)(DIR ? (4095 - q0) : q0) * 1024] = f2bf(ykeep); }
;     RW_STEP(17, WvB, XB, KrB, vhB, WvA, XA, KrA, vhA);
;     RW_STEP2(18); RW_STEP4(20); RW_STEP4(24); RW_STEP4(28);
;   }
	ds_read_b128 v[100:103], v9
	ds_read_b128 v[104:107], v9 offset:16
	v_fma_mix_f32 v14, v10, v122, 0 op_sel:[0,0,0] op_sel_hi:[0,1,0]
	v_fma_mix_f32 v60, v10, v116, 0 op_sel:[0,0,0] op_sel_hi:[0,1,0]
	v_fma_mix_f32 v14, v11, v122, v14 op_sel:[0,1,0] op_sel_hi:[0,1,0]
	v_fma_mix_f32 v60, v11, v116, v60 op_sel:[0,1,0] op_sel_hi:[0,1,0]
	v_fma_mix_f32 v14, v12, v123, v14 op_sel:[0,0,0] op_sel_hi:[0,1,0]
	v_fma_mix_f32 v60, v12, v117, v60 op_sel:[0,0,0] op_sel_hi:[0,1,0]
	v_fma_mix_f32 v14, v13, v123, v14 op_sel:[0,1,0] op_sel_hi:[0,1,0]
	v_fma_mix_f32 v16, v10, v120, 0 op_sel:[0,0,0] op_sel_hi:[0,1,0]
	v_fma_mix_f32 v17, v11, v120, 0 op_sel:[0,1,0] op_sel_hi:[0,1,0]
	v_add_f32_dpp v20, v14, v14 quad_perm:[1,0,3,2] row_mask:0xf bank_mask:0xf bound_ctrl:1
	v_fma_mix_f32 v60, v13, v117, v60 op_sel:[0,1,0] op_sel_hi:[0,1,0]
	v_fma_mix_f32 v18, v12, v121, 0 op_sel:[0,0,0] op_sel_hi:[0,1,0]
	v_add_f32_dpp v20, v20, v20 quad_perm:[2,3,0,1] row_mask:0xf bank_mask:0xf bound_ctrl:1
	v_fma_mix_f32 v19, v13, v121, 0 op_sel:[0,1,0] op_sel_hi:[0,1,0]
	v_fma_mix_f32 v16, v130, v126, v16 op_sel:[0,0,0] op_sel_hi:[1,1,0]
	v_add_f32_dpp v20, v20, v20 row_half_mirror row_mask:0xf bank_mask:0xf bound_ctrl:1
	v_fma_mix_f32 v17, v130, v126, v17 op_sel:[0,1,0] op_sel_hi:[1,1,0]
	v_fma_mix_f32 v18, v130, v127, v18 op_sel:[0,0,0] op_sel_hi:[1,1,0]
	v_add_f32_dpp v20, v20, v20 row_mirror row_mask:0xf bank_mask:0xf bound_ctrl:1
	v_fma_mix_f32 v19, v130, v127, v19 op_sel:[0,1,0] op_sel_hi:[1,1,0]
	v_fma_mix_f32 v10, v20, v124, v16 op_sel:[0,0,0] op_sel_hi:[0,1,0]
	v_fma_mix_f32 v11, v20, v124, v17 op_sel:[0,1,0] op_sel_hi:[0,1,0]
	v_fma_mix_f32 v12, v20, v125, v18 op_sel:[0,0,0] op_sel_hi:[0,1,0]
	v_fma_mix_f32 v13, v20, v125, v19 op_sel:[0,1,0] op_sel_hi:[0,1,0]
	s_waitcnt lgkmcnt(6)
	v_add_u32_e32 v6, 0x4000, v6
	v_add_u32_e32 v7, 0x4000, v7
	v_and_b32_e32 v6, 0x1ffff, v6
	v_and_b32_e32 v7, 0x1ffff, v7
	ds_read_b64 v[24:25], v6 offset:16
	ds_read_b128 v[26:29], v6 offset:272
	ds_read_b128 v[30:33], v6 offset:528
	ds_read_u16 v34, v7 offset:16
	ds_read_b64 v[36:37], v6 offset:1040
	ds_read_b128 v[38:41], v6 offset:1296
	ds_read_b128 v[42:45], v6 offset:1552
	ds_read_u16 v46, v7 offset:1040
	v_fma_mix_f32 v14, v10, v134, 0 op_sel:[0,0,0] op_sel_hi:[0,1,0]
	v_fma_mix_f32 v61, v10, v128, 0 op_sel:[0,0,0] op_sel_hi:[0,1,0]
	v_fma_mix_f32 v14, v11, v134, v14 op_sel:[0,1,0] op_sel_hi:[0,1,0]
	v_fma_mix_f32 v61, v11, v128, v61 op_sel:[0,1,0] op_sel_hi:[0,1,0]
	v_fma_mix_f32 v14, v12, v135, v14 op_sel:[0,0,0] op_sel_hi:[0,1,0]
	v_fma_mix_f32 v61, v12, v129, v61 op_sel:[0,0,0] op_sel_hi:[0,1,0]
	v_fma_mix_f32 v14, v13, v135, v14 op_sel:[0,1,0] op_sel_hi:[0,1,0]
	v_fma_mix_f32 v16, v10, v132, 0 op_sel:[0,0,0] op_sel_hi:[0,1,0]
	v_fma_mix_f32 v17, v11, v132, 0 op_sel:[0,1,0] op_sel_hi:[0,1,0]
	v_add_f32_dpp v20, v14, v14 quad_perm:[1,0,3,2] row_mask:0xf bank_mask:0xf bound_ctrl:1
	v_fma_mix_f32 v61, v13, v129, v61 op_sel:[0,1,0] op_sel_hi:[0,1,0]
	v_fma_mix_f32 v18, v12, v133, 0 op_sel:[0,0,0] op_sel_hi:[0,1,0]
	v_add_f32_dpp v20, v20, v20 quad_perm:[2,3,0,1] row_mask:0xf bank_mask:0xf bound_ctrl:1
	v_fma_mix_f32 v19, v13, v133, 0 op_sel:[0,1,0] op_sel_hi:[0,1,0]
	v_fma_mix_f32 v16, v142, v138, v16 op_sel:[0,0,0] op_sel_hi:[1,1,0]
	v_add_f32_dpp v20, v20, v20 row_half_mirror row_mask:0xf bank_mask:0xf bound_ctrl:1
	v_fma_mix_f32 v17, v142, v138, v17 op_sel:[0,1,0] op_sel_hi:[1,1,0]
	v_fma_mix_f32 v18, v142, v139, v18 op_sel:[0,0,0] op_sel_hi:[1,1,0]
	v_add_f32_dpp v20, v20, v20 row_mirror row_mask:0xf bank_mask:0xf bound_ctrl:1
	v_fma_mix_f32 v19, v142, v139, v19 op_sel:[0,1,0] op_sel_hi:[1,1,0]
	v_fma_mix_f32 v10, v20, v136, v16 op_sel:[0,0,0] op_sel_hi:[0,1,0]
	v_fma_mix_f32 v11, v20, v136, v17 op_sel:[0,1,0] op_sel_hi:[0,1,0]
	v_fma_mix_f32 v12, v20, v137, v18 op_sel:[0,0,0] op_sel_hi:[0,1,0]
	v_fma_mix_f32 v13, v20, v137, v19 op_sel:[0,1,0] op_sel_hi:[0,1,0]
	s_waitcnt lgkmcnt(8)
	v_fma_mix_f32 v14, v10, v146, 0 op_sel:[0,0,0] op_sel_hi:[0,1,0]
	v_fma_mix_f32 v62, v10, v140, 0 op_sel:[0,0,0] op_sel_hi:[0,1,0]
	v_fma_mix_f32 v14, v11, v146, v14 op_sel:[0,1,0] op_sel_hi:[0,1,0]
	v_fma_mix_f32 v62, v11, v140, v62 op_sel:[0,1,0] op_sel_hi:[0,1,0]
	v_fma_mix_f32 v14, v12, v147, v14 op_sel:[0,0,0] op_sel_hi:[0,1,0]
	v_fma_mix_f32 v62, v12, v141, v62 op_sel:[0,0,0] op_sel_hi:[0,1,0]
	v_fma_mix_f32 v14, v13, v147, v14 op_sel:[0,1,0] op_sel_hi:[0,1,0]
	v_fma_mix_f32 v16, v10, v144, 0 op_sel:[0,0,0] op_sel_hi:[0,1,0]
	v_fma_mix_f32 v17, v11, v144, 0 op_sel:[0,1,0] op_sel_hi:[0,1,0]
	v_add_f32_dpp v20, v14, v14 quad_perm:[1,0,3,2] row_mask:0xf bank_mask:0xf bound_ctrl:1
	v_fma_mix_f32 v62, v13, v141, v62 op_sel:[0,1,0] op_sel_hi:[0,1,0]
	v_fma_mix_f32 v18, v12, v145, 0 op_sel:[0,0,0] op_sel_hi:[0,1,0]
	v_add_f32_dpp v20, v20, v20 quad_perm:[2,3,0,1] row_mask:0xf bank_mask:0xf bound_ctrl:1
	v_fma_mix_f32 v19, v13, v145, 0 op_sel:[0,1,0] op_sel_hi:[0,1,0]
	v_fma_mix_f32 v16, v154, v150, v16 op_sel:[0,0,0] op_sel_hi:[1,1,0]
	v_add_f32_dpp v20, v20, v20 row_half_mirror row_mask:0xf bank_mask:0xf bound_ctrl:1
	v_fma_mix_f32 v17, v154, v150, v17 op_sel:[0,1,0] op_sel_hi:[1,1,0]
	v_fma_mix_f32 v18, v154, v151, v18 op_sel:[0,0,0] op_sel_hi:[1,1,0]
	v_add_f32_dpp v20, v20, v20 row_mirror row_mask:0xf bank_mask:0xf bound_ctrl:1
	v_fma_mix_f32 v19, v154, v151, v19 op_sel:[0,1,0] op_sel_hi:[1,1,0]
	v_fma_mix_f32 v10, v20, v148, v16 op_sel:[0,0,0] op_sel_hi:[0,1,0]
	v_fma_mix_f32 v11, v20, v148, v17 op_sel:[0,1,0] op_sel_hi:[0,1,0]
	v_fma_mix_f32 v12, v20, v149, v18 op_sel:[0,0,0] op_sel_hi:[0,1,0]
	v_fma_mix_f32 v13, v20, v149, v19 op_sel:[0,1,0] op_sel_hi:[0,1,0]
	s_waitcnt lgkmcnt(4)
	s_add_u32 s15, s15, 1
	s_add_u32 s14, s14, 1
	v_mov_b32_e32 v69, s15
	ds_write_b32 v68, v69
	s_cmp_lt_u32 s14, 0x100
	s_cbranch_scc1 .Lrw_blk_d0
; DEVINL u16 f2bf(float a) { return (u16)(pk2(a, 0.f) & 0xffffu); }
; template <int DIR>
; DEVINL void rwkv_scan_dir(const Params& p, int task, int lane, int wave) {
;     ...
;   {
;     const float ylast = allred16(ypart);
;     ykeep = (seg == 15) ? ylast : ykeep;
;     const int q0 = 4096 - 16 + seg; yo[(long)(DIR ? (4095 - q0) : q0) * 1024] = f2bf(ykeep);
;   }
;   asm volatile("s_waitcnt vmcnt(0)" ::: "memory");
	v_fma_mix_f32 v21, v10, v152, 0 op_sel:[0,0,0] op_sel_hi:[0,1,0]
	v_fma_mix_f32 v22, v12, v153, 0 op_sel:[0,0,0] op_sel_hi:[0,1,0]
	v_fma_mix_f32 v21, v11, v152, v21 op_sel:[0,1,0] op_sel_hi:[0,1,0]
	v_fma_mix_f32 v22, v13, v153, v22 op_sel:[0,1,0] op_sel_hi:[0,1,0]
	v_add_f32_e32 v63, v21, v22
	s_nop 1
	v_add_f32_dpp v48, v48, v48 row_ror:8 row_mask:0xf bank_mask:0x3
	v_add_f32_dpp v49, v49, v49 row_ror:8 row_mask:0xf bank_mask:0x3
	v_add_f32_dpp v50, v50, v50 row_ror:8 row_mask:0xf bank_mask:0x3
	v_add_f32_dpp v51, v51, v51 row_ror:8 row_mask:0xf bank_mask:0x3
	v_add_f32_dpp v52, v52, v52 row_ror:8 row_mask:0xf bank_mask:0x3
	v_add_f32_dpp v53, v53, v53 row_ror:8 row_mask:0xf bank_mask:0x3
	v_add_f32_dpp v54, v54, v54 row_ror:8 row_mask:0xf bank_mask:0x3
	v_add_f32_dpp v55, v55, v55 row_ror:8 row_mask:0xf bank_mask:0x3
	v_add_f32_dpp v48, v56, v56 row_ror:8 row_mask:0xf bank_mask:0xc
	v_add_f32_dpp v49, v57, v57 row_ror:8 row_mask:0xf bank_mask:0xc
	v_add_f32_dpp v50, v58, v58 row_ror:8 row_mask:0xf bank_mask:0xc
	v_add_f32_dpp v51, v59, v59 row_ror:8 row_mask:0xf bank_mask:0xc
	v_add_f32_dpp v52, v60, v60 row_ror:8 row_mask:0xf bank_mask:0xc
	v_add_f32_dpp v53, v61, v61 row_ror:8 row_mask:0xf bank_mask:0xc
	v_add_f32_dpp v54, v62, v62 row_ror:8 row_mask:0xf bank_mask:0xc
	v_add_f32_dpp v55, v63, v63 row_ror:8 row_mask:0xf bank_mask:0xc
	v_add_f32_dpp v48, v48, v48 row_ror:12 row_mask:0xf bank_mask:0x5
	v_add_f32_dpp v49, v49, v49 row_ror:12 row_mask:0xf bank_mask:0x5
	v_add_f32_dpp v50, v50, v50 row_ror:12 row_mask:0xf bank_mask:0x5
	v_add_f32_dpp v51, v51, v51 row_ror:12 row_mask:0xf bank_mask:0x5
	v_add_f32_dpp v48, v52, v52 row_ror:4 row_mask:0xf bank_mask:0xa
	v_add_f32_dpp v49, v53, v53 row_ror:4 row_mask:0xf bank_mask:0xa
	v_add_f32_dpp v50, v54, v54 row_ror:4 row_mask:0xf bank_mask:0xa
	v_add_f32_dpp v51, v55, v55 row_ror:4 row_mask:0xf bank_mask:0xa
	v_add_f32_dpp v64, v48, v48 quad_perm:[2,3,0,1] row_mask:0xf bank_mask:0xf bound_ctrl:1
	v_add_f32_dpp v65, v50, v50 quad_perm:[2,3,0,1] row_mask:0xf bank_mask:0xf bound_ctrl:1
	v_cndmask_b32_e64 v56, v64, v65, s[50:51]
	v_add_f32_dpp v64, v49, v49 quad_perm:[2,3,0,1] row_mask:0xf bank_mask:0xf bound_ctrl:1
	v_add_f32_dpp v65, v51, v51 quad_perm:[2,3,0,1] row_mask:0xf bank_mask:0xf bound_ctrl:1
	v_cndmask_b32_e64 v57, v64, v65, s[50:51]
	v_add_f32_dpp v64, v56, v56 quad_perm:[1,0,3,2] row_mask:0xf bank_mask:0xf bound_ctrl:1
	s_nop 0
	v_add_f32_dpp v65, v57, v57 quad_perm:[1,0,3,2] row_mask:0xf bank_mask:0xf bound_ctrl:1
	v_cndmask_b32_e64 v66, v64, v65, s[48:49]
	v_cvt_pk_bf16_f32 v66, v66, v66
	global_store_short v8, v66, s[12:13]
	s_add_u32 s12, s12, 0x8000
	s_addc_u32 s13, s13, 0
	s_branch .Lrw_next

; DEVINL u16 f2bf(float a) { return (u16)(pk2(a, 0.f) & 0xffffu); }
; #define RW_STEP2(B) RW_STEP(B, WvA, XA, KrA, vhA, WvB, XB, KrB, vhB); RW_STEP((B) + 1, WvB, XB, KrB, vhB, WvA, XA, KrA, vhA)
; #define RW_STEP4(B) RW_STEP2(B); RW_STEP2((B) + 2)
; template <int DIR>
; DEVINL void rwkv_scan_dir(const Params& p, int task, int lane, int wave) {
;     ...
;     if (st > 0) { const int q0 = st - 16 + seg; yo[(long)(DIR ? (4095 - q0) : q0) * 1024] = f2bf(ykeep); }
;     RW_STEP(1, WvB, XB, KrB, vhB, WvA, XA, KrA, vhA);
;     RW_STEP2(2); RW_STEP4(4); RW_STEP4(8); RW_STEP4(12);
;     RW_STEP(16, WvA, XA, KrA, vhA, WvB, XB, KrB, vhB);
;     { const int q0 = st + seg; yo[(long)(DIR ? (4095 - q0) : q0) * 1024] = f2bf(ykeep); }
.Lrw_ready_d1:
	s_add_u32 s3, s40, s41
	s_and_b32 s3, s3, 0x1ffff
	s_add_u32 s3, s3, 16
	s_mov_b32 m0, s3
	s_nop 0
	global_load_lds_dwordx4 v5, s[10:11] offset:0
	global_load_lds_dwordx4 v5, s[10:11] offset:1024
	global_load_lds_dwordx4 v5, s[10:11] offset:2048
	global_load_lds_dwordx4 v5, s[10:11] offset:3072
	s_sub_u32 s10, s10, 0x4000
	s_subb_u32 s11, s11, 0
	s_sub_u32 s41, s41, 0x4000
	s_and_b32 s41, s41, 0x1ffff
	ds_read_b64 v[72:73], v6 offset:13336
	ds_read_b128 v[74:77], v6 offset:13584
	ds_read_b128 v[78:81], v6 offset:13840
	ds_read_u16 v82, v7 offset:13328
	ds_read_b64 v[84:85], v6 offset:12312
	ds_read_b128 v[86:89], v6 offset:12560
	ds_read_b128 v[90:93], v6 offset:12816
	ds_read_u16 v94, v7 offset:12304
	v_fma_mix_f32 v14, v10, v26, 0 op_sel:[0,0,0] op_sel_hi:[0,1,0]
	v_fma_mix_f32 v63, v10, v152, 0 op_sel:[0,0,0] op_sel_hi:[0,1,0]
	v_fma_mix_f32 v14, v11, v26, v14 op_sel:[0,1,0] op_sel_hi:[0,1,0]
	v_fma_mix_f32 v63, v11, v152, v63 op_sel:[0,1,0] op_sel_hi:[0,1,0]
	v_fma_mix_f32 v14, v12, v27, v14 op_sel:[0,0,0] op_sel_hi:[0,1,0]
	v_fma_mix_f32 v63, v12, v153, v63 op_sel:[0,0,0] op_sel_hi:[0,1,0]
	v_fma_mix_f32 v14, v13, v27, v14 op_sel:[0,1,0] op_sel_hi:[0,1,0]
	v_fma_mix_f32 v16, v10, v24, 0 op_sel:[0,0,0] op_sel_hi:[0,1,0]
	v_fma_mix_f32 v17, v11, v24, 0 op_sel:[0,1,0] op_sel_hi:[0,1,0]
	v_add_f32_dpp v20, v14, v14 quad_perm:[1,0,3,2] row_mask:0xf bank_mask:0xf bound_ctrl:1
	v_fma_mix_f32 v63, v13, v153, v63 op_sel:[0,1,0] op_sel_hi:[0,1,0]
	v_fma_mix_f32 v18, v12, v25, 0 op_sel:[0,0,0] op_sel_hi:[0,1,0]
	v_add_f32_dpp v20, v20, v20 quad_perm:[2,3,0,1] row_mask:0xf bank_mask:0xf bound_ctrl:1
	v_fma_mix_f32 v19, v13, v25, 0 op_sel:[0,1,0] op_sel_hi:[0,1,0]
	v_fma_mix_f32 v16, v34, v30, v16 op_sel:[0,0,0] op_sel_hi:[1,1,0]
	v_add_f32_dpp v20, v20, v20 row_half_mirror row_mask:0xf bank_mask:0xf bound_ctrl:1
	v_fma_mix_f32 v17, v34, v30, v17 op_sel:[0,1,0] op_sel_hi:[1,1,0]
	v_fma_mix_f32 v18, v34, v31, v18 op_sel:[0,0,0] op_sel_hi:[1,1,0]
	v_add_f32_dpp v20, v20, v20 row_mirror row_mask:0xf bank_mask:0xf bound_ctrl:1
	v_fma_mix_f32 v19, v34, v31, v19 op_sel:[0,1,0] op_sel_hi:[1,1,0]
	v_fma_mix_f32 v10, v20, v28, v16 op_sel:[0,0,0] op_sel_hi:[0,1,0]
	v_fma_mix_f32 v11, v20, v28, v17 op_sel:[0,1,0] op_sel_hi:[0,1,0]
	v_fma_mix_f32 v12, v20, v29, v18 op_sel:[0,0,0] op_sel_hi:[0,1,0]
	v_fma_mix_f32 v13, v20, v29, v19 op_sel:[0,1,0] op_sel_hi:[0,1,0]
	s_waitcnt lgkmcnt(8)
	s_cmp_eq_u32 s14, 0
	s_cbranch_scc1 .Lrw_skip_d1
	v_add_f32_dpp v48, v48, v48 row_ror:8 row_mask:0xf bank_mask:0x3
	v_add_f32_dpp v49, v49, v49 row_ror:8 row_mask:0xf bank_mask:0x3
	v_add_f32_dpp v50, v50, v50 row_ror:8 row_mask:0xf bank_mask:0x3
	v_add_f32_dpp v51, v51, v51 row_ror:8 row_mask:0xf bank_mask:0x3
	v_add_f32_dpp v52, v52, v52 row_ror:8 row_mask:0xf bank_mask:0x3
	v_add_f32_dpp v53, v53, v53 row_ror:8 row_mask:0xf bank_mask:0x3
	v_add_f32_dpp v54, v54, v54 row_ror:8 row_mask:0xf bank_mask:0x3
	v_add_f32_dpp v55, v55, v55 row_ror:8 row_mask:0xf bank_mask:0x3
	v_add_f32_dpp v48, v56, v56 row_ror:8 row_mask:0xf bank_mask:0xc
	v_add_f32_dpp v49, v57, v57 row_ror:8 row_mask:0xf bank_mask:0xc
	v_add_f32_dpp v50, v58, v58 row_ror:8 row_mask:0xf bank_mask:0xc
	v_add_f32_dpp v51, v59, v59 row_ror:8 row_mask:0xf bank_mask:0xc
	v_add_f32_dpp v52, v60, v60 row_ror:8 row_mask:0xf bank_mask:0xc
	v_add_f32_dpp v53, v61, v61 row_ror:8 row_mask:0xf bank_mask:0xc
	v_add_f32_dpp v54, v62, v62 row_ror:8 row_mask:0xf bank_mask:0xc
	v_add_f32_dpp v55, v63, v63 row_ror:8 row_mask:0xf bank_mask:0xc
	v_add_f32_dpp v48, v48, v48 row_ror:12 row_mask:0xf bank_mask:0x5
	v_add_f32_dpp v49, v49, v49 row_ror:12 row_mask:0xf bank_mask:0x5
	v_add_f32_dpp v50, v50, v50 row_ror:12 row_mask:0xf bank_mask:0x5
	v_add_f32_dpp v51, v51, v51 row_ror:12 row_mask:0xf bank_mask:0x5
	v_add_f32_dpp v48, v52, v52 row_ror:4 row_mask:0xf bank_mask:0xa
	v_add_f32_dpp v49, v53, v53 row_ror:4 row_mask:0xf bank_mask:0xa
	v_add_f32_dpp v50, v54, v54 row_ror:4 row_mask:0xf bank_mask:0xa
	v_add_f32_dpp v51, v55, v55 row_ror:4 row_mask:0xf bank_mask:0xa
	v_add_f32_dpp v64, v48, v48 quad_perm:[2,3,0,1] row_mask:0xf bank_mask:0xf bound_ctrl:1
	v_add_f32_dpp v65, v50, v50 quad_perm:[2,3,0,1] row_mask:0xf bank_mask:0xf bound_ctrl:1
	v_cndmask_b32_e64 v56, v64, v65, s[50:51]
	v_add_f32_dpp v64, v49, v49 quad_perm:[2,3,0,1] row_mask:0xf bank_mask:0xf bound_ctrl:1
	v_add_f32_dpp v65, v51, v51 quad_perm:[2,3,0,1] row_mask:0xf bank_mask:0xf bound_ctrl:1
	v_cndmask_b32_e64 v57, v64, v65, s[50:51]
	v_add_f32_dpp v64, v56, v56 quad_perm:[1,0,3,2] row_mask:0xf bank_mask:0xf bound_ctrl:1
	s_nop 0
	v_add_f32_dpp v65, v57, v57 quad_perm:[1,0,3,2] row_mask:0xf bank_mask:0xf bound_ctrl:1
	v_cndmask_b32_e64 v66, v64, v65, s[48:49]
	v_cvt_pk_bf16_f32 v66, v66, v66
	global_store_short v8, v66, s[12:13]
	s_sub_u32 s12, s12, 0x8000
	s_subb_u32 s13, s13, 0
.Lrw_skip_d1:
	v_fma_mix_f32 v14, v10, v38, 0 op_sel:[0,0,0] op_sel_hi:[0,1,0]
	v_fma_mix_f32 v48, v10, v32, 0 op_sel:[0,0,0] op_sel_hi:[0,1,0]
	v_fma_mix_f32 v14, v11, v38, v14 op_sel:[0,1,0] op_sel_hi:[0,1,0]
	v_fma_mix_f32 v48, v11, v32, v48 op_sel:[0,1,0] op_sel_hi:[0,1,0]
	v_fma_mix_f32 v14, v12, v39, v14 op_sel:[0,0,0] op_sel_hi:[0,1,0]
	v_fma_mix_f32 v48, v12, v33, v48 op_sel:[0,0,0] op_sel_hi:[0,1,0]
	v_fma_mix_f32 v14, v13, v39, v14 op_sel:[0,1,0] op_sel_hi:[0,1,0]
	v_fma_mix_f32 v16, v10, v36, 0 op_sel:[0,0,0] op_sel_hi:[0,1,0]
	v_fma_mix_f32 v17, v11, v36, 0 op_sel:[0,1,0] op_sel_hi:[0,1,0]
	v_add_f32_dpp v20, v14, v14 quad_perm:[1,0,3,2] row_mask:0xf bank_mask:0xf bound_ctrl:1
	v_fma_mix_f32 v48, v13, v33, v48 op_sel:[0,1,0] op_sel_hi:[0,1,0]
	v_fma_mix_f32 v18, v12, v37, 0 op_sel:[0,0,0] op_sel_hi:[0,1,0]
	v_add_f32_dpp v20, v20, v20 quad_perm:[2,3,0,1] row_mask:0xf bank_mask:0xf bound_ctrl:1
	v_fma_mix_f32 v19, v13, v37, 0 op_sel:[0,1,0] op_sel_hi:[0,1,0]
	v_fma_mix_f32 v16, v46, v42, v16 op_sel:[0,0,0] op_sel_hi:[1,1,0]
	v_add_f32_dpp v20, v20, v20 row_half_mirror row_mask:0xf bank_mask:0xf bound_ctrl:1
	v_fma_mix_f32 v17, v46, v42, v17 op_sel:[0,1,0] op_sel_hi:[1,1,0]
	v_fma_mix_f32 v18, v46, v43, v18 op_sel:[0,0,0] op_sel_hi:[1,1,0]
	v_add_f32_dpp v20, v20, v20 row_mirror row_mask:0xf bank_mask:0xf bound_ctrl:1
	v_fma_mix_f32 v19, v46, v43, v19 op_sel:[0,1,0] op_sel_hi:[1,1,0]
	v_fma_mix_f32 v10, v20, v40, v16 op_sel:[0,0,0] op_sel_hi:[0,1,0]
	v_fma_mix_f32 v11, v20, v40, v17 op_sel:[0,1,0] op_sel_hi:[0,1,0]
	v_fma_mix_f32 v12, v20, v41, v18 op_sel:[0,0,0] op_sel_hi:[0,1,0]
	v_fma_mix_f32 v13, v20, v41, v19 op_sel:[0,1,0] op_sel_hi:[0,1,0]
	s_waitcnt lgkmcnt(4)
	ds_read_b64 v[108:109], v6 offset:11288
	ds_read_b128 v[110:113], v6 offset:11536
	ds_read_b128 v[114:117], v6 offset:11792
	ds_read_u16 v118, v7 offset:11280
	ds_read_b64 v[120:121], v6 offset:10264
	ds_read_b128 v[122:125], v6 offset:10512
	ds_read_b128 v[126:129], v6 offset:10768
	ds_read_u16 v130, v7 offset:10256
	v_fma_mix_f32 v14, v10, v74, 0 op_sel:[0,0,0] op_sel_hi:[0,1,0]
	v_fma_mix_f32 v49, v10, v44, 0 op_sel:[0,0,0] op_sel_hi:[0,1,0]
	v_fma_mix_f32 v14, v11, v74, v14 op_sel:[0,1,0] op_sel_hi:[0,1,0]
	v_fma_mix_f32 v49, v11, v44, v49 op_sel:[0,1,0] op_sel_hi:[0,1,0]
	v_fma_mix_f32 v14, v12, v75, v14 op_sel:[0,0,0] op_sel_hi:[0,1,0]
	v_fma_mix_f32 v49, v12, v45, v49 op_sel:[0,0,0] op_sel_hi:[0,1,0]
	v_fma_mix_f32 v14, v13, v75, v14 op_sel:[0,1,0] op_sel_hi:[0,1,0]
	v_fma_mix_f32 v16, v10, v72, 0 op_sel:[0,0,0] op_sel_hi:[0,1,0]
	v_fma_mix_f32 v17, v11, v72, 0 op_sel:[0,1,0] op_sel_hi:[0,1,0]
	v_add_f32_dpp v20, v14, v14 quad_perm:[1,0,3,2] row_mask:0xf bank_mask:0xf bound_ctrl:1
	v_fma_mix_f32 v49, v13, v45, v49 op_sel:[0,1,0] op_sel_hi:[0,1,0]
	v_fma_mix_f32 v18, v12, v73, 0 op_sel:[0,0,0] op_sel_hi:[0,1,0]
	v_add_f32_dpp v20, v20, v20 quad_perm:[2,3,0,1] row_mask:0xf bank_mask:0xf bound_ctrl:1
	v_fma_mix_f32 v19, v13, v73, 0 op_sel:[0,1,0] op_sel_hi:[0,1,0]
	v_fma_mix_f32 v16, v82, v78, v16 op_sel:[0,0,0] op_sel_hi:[1,1,0]
	v_add_f32_dpp v20, v20, v20 row_half_mirror row_mask:0xf bank_mask:0xf bound_ctrl:1
	v_fma_mix_f32 v17, v82, v78, v17 op_sel:[0,1,0] op_sel_hi:[1,1,0]
	v_fma_mix_f32 v18, v82, v79, v18 op_sel:[0,0,0] op_sel_hi:[1,1,0]
	v_add_f32_dpp v20, v20, v20 row_mirror row_mask:0xf bank_mask:0xf bound_ctrl:1
	v_fma_mix_f32 v19, v82, v79, v19 op_sel:[0,1,0] op_sel_hi:[1,1,0]
	v_fma_mix_f32 v10, v20, v76, v16 op_sel:[0,0,0] op_sel_hi:[0,1,0]
	v_fma_mix_f32 v11, v20, v76, v17 op_sel:[0,1,0] op_sel_hi:[0,1,0]
	v_fma_mix_f32 v12, v20, v77, v18 op_sel:[0,0,0] op_sel_hi:[0,1,0]
	v_fma_mix_f32 v13, v20, v77, v19 op_sel:[0,1,0] op_sel_hi:[0,1,0]
	s_waitcnt lgkmcnt(8)
	v_fma_mix_f32 v14, v10, v86, 0 op_sel:[0,0,0] op_sel_hi:[0,1,0]
	v_fma_mix_f32 v50, v10, v80, 0 op_sel:[0,0,0] op_sel_hi:[0,1,0]
	v_fma_mix_f32 v14, v11, v86, v14 op_sel:[0,1,0] op_sel_hi:[0,1,0]
	v_fma_mix_f32 v50, v11, v80, v50 op_sel:[0,1,0] op_sel_hi:[0,1,0]
	v_fma_mix_f32 v14, v12, v87, v14 op_sel:[0,0,0] op_sel_hi:[0,1,0]
	v_fma_mix_f32 v50, v12, v81, v50 op_sel:[0,0,0] op_sel_hi:[0,1,0]
	v_fma_mix_f32 v14, v13, v87, v14 op_sel:[0,1,0] op_sel_hi:[0,1,0]
	v_fma_mix_f32 v16, v10, v84, 0 op_sel:[0,0,0] op_sel_hi:[0,1,0]
	v_fma_mix_f32 v17, v11, v84, 0 op_sel:[0,1,0] op_sel_hi:[0,1,0]
	v_add_f32_dpp v20, v14, v14 quad_perm:[1,0,3,2] row_mask:0xf bank_mask:0xf bound_ctrl:1
	v_fma_mix_f32 v50, v13, v81, v50 op_sel:[0,1,0] op_sel_hi:[0,1,0]
	v_fma_mix_f32 v18, v12, v85, 0 op_sel:[0,0,0] op_sel_hi:[0,1,0]
	v_add_f32_dpp v20, v20, v20 quad_perm:[2,3,0,1] row_mask:0xf bank_mask:0xf bound_ctrl:1
	v_fma_mix_f32 v19, v13, v85, 0 op_sel:[0,1,0] op_sel_hi:[0,1,0]
	v_fma_mix_f32 v16, v94, v90, v16 op_sel:[0,0,0] op_sel_hi:[1,1,0]
	v_add_f32_dpp v20, v20, v20 row_half_mirror row_mask:0xf bank_mask:0xf bound_ctrl:1
	v_fma_mix_f32 v17, v94, v90, v17 op_sel:[0,1,0] op_sel_hi:[1,1,0]
	v_fma_mix_f32 v18, v94, v91, v18 op_sel:[0,0,0] op_sel_hi:[1,1,0]
	v_add_f32_dpp v20, v20, v20 row_mirror row_mask:0xf bank_mask:0xf bound_ctrl:1
	v_fma_mix_f32 v19, v94, v91, v19 op_sel:[0,1,0] op_sel_hi:[1,1,0]
	v_fma_mix_f32 v10, v20, v88, v16 op_sel:[0,0,0] op_sel_hi:[0,1,0]
	v_fma_mix_f32 v11, v20, v88, v17 op_sel:[0,1,0] op_sel_hi:[0,1,0]
	v_fma_mix_f32 v12, v20, v89, v18 op_sel:[0,0,0] op_sel_hi:[0,1,0]
	v_fma_mix_f32 v13, v20, v89, v19 op_sel:[0,1,0] op_sel_hi:[0,1,0]
	s_waitcnt lgkmcnt(4)
	ds_read_b64 v[132:133], v6 offset:9240
	ds_read_b128 v[134:137], v6 offset:9488
	ds_read_b128 v[138:141], v6 offset:9744
	ds_read_u16 v142, v7 offset:9232
	ds_read_b64 v[144:145], v6 offset:8216
	ds_read_b128 v[146:149], v6 offset:8464
	ds_read_b128 v[150:153], v6 offset:8720
	ds_read_u16 v154, v7 offset:8208
	v_fma_mix_f32 v14, v10, v110, 0 op_sel:[0,0,0] op_sel_hi:[0,1,0]
	v_fma_mix_f32 v51, v10, v92, 0 op_sel:[0,0,0] op_sel_hi:[0,1,0]
	v_fma_mix_f32 v14, v11, v110, v14 op_sel:[0,1,0] op_sel_hi:[0,1,0]
	v_fma_mix_f32 v51, v11, v92, v51 op_sel:[0,1,0] op_sel_hi:[0,1,0]
	v_fma_mix_f32 v14, v12, v111, v14 op_sel:[0,0,0] op_sel_hi:[0,1,0]
	v_fma_mix_f32 v51, v12, v93, v51 op_sel:[0,0,0] op_sel_hi:[0,1,0]
	v_fma_mix_f32 v14, v13, v111, v14 op_sel:[0,1,0] op_sel_hi:[0,1,0]
	v_fma_mix_f32 v16, v10, v108, 0 op_sel:[0,0,0] op_sel_hi:[0,1,0]
	v_fma_mix_f32 v17, v11, v108, 0 op_sel:[0,1,0] op_sel_hi:[0,1,0]
	v_add_f32_dpp v20, v14, v14 quad_perm:[1,0,3,2] row_mask:0xf bank_mask:0xf bound_ctrl:1
	v_fma_mix_f32 v51, v13, v93, v51 op_sel:[0,1,0] op_sel_hi:[0,1,0]
	v_fma_mix_f32 v18, v12, v109, 0 op_sel:[0,0,0] op_sel_hi:[0,1,0]
	v_add_f32_dpp v20, v20, v20 quad_perm:[2,3,0,1] row_mask:0xf bank_mask:0xf bound_ctrl:1
	v_fma_mix_f32 v19, v13, v109, 0 op_sel:[0,1,0] op_sel_hi:[0,1,0]
	v_fma_mix_f32 v16, v118, v114, v16 op_sel:[0,0,0] op_sel_hi:[1,1,0]
	v_add_f32_dpp v20, v20, v20 row_half_mirror row_mask:0xf bank_mask:0xf bound_ctrl:1
	v_fma_mix_f32 v17, v118, v114, v17 op_sel:[0,1,0] op_sel_hi:[1,1,0]
	v_fma_mix_f32 v18, v118, v115, v18 op_sel:[0,0,0] op_sel_hi:[1,1,0]
	v_add_f32_dpp v20, v20, v20 row_mirror row_mask:0xf bank_mask:0xf bound_ctrl:1
	v_fma_mix_f32 v19, v118, v115, v19 op_sel:[0,1,0] op_sel_hi:[1,1,0]
	v_fma_mix_f32 v10, v20, v112, v16 op_sel:[0,0,0] op_sel_hi:[0,1,0]
	v_fma_mix_f32 v11, v20, v112, v17 op_sel:[0,1,0] op_sel_hi:[0,1,0]
	v_fma_mix_f32 v12, v20, v113, v18 op_sel:[0,0,0] op_sel_hi:[0,1,0]
	v_fma_mix_f32 v13, v20, v113, v19 op_sel:[0,1,0] op_sel_hi:[0,1,0]
	s_waitcnt lgkmcnt(8)
	v_fma_mix_f32 v14, v10, v122, 0 op_sel:[0,0,0] op_sel_hi:[0,1,0]
	v_fma_mix_f32 v52, v10, v116, 0 op_sel:[0,0,0] op_sel_hi:[0,1,0]
	v_fma_mix_f32 v14, v11, v122, v14 op_sel:[0,1,0] op_sel_hi:[0,1,0]
	v_fma_mix_f32 v52, v11, v116, v52 op_sel:[0,1,0] op_sel_hi:[0,1,0]
	v_fma_mix_f32 v14, v12, v123, v14 op_sel:[0,0,0] op_sel_hi:[0,1,0]
	v_fma_mix_f32 v52, v12, v117, v52 op_sel:[0,0,0] op_sel_hi:[0,1,0]
	v_fma_mix_f32 v14, v13, v123, v14 op_sel:[0,1,0] op_sel_hi:[0,1,0]
	v_fma_mix_f32 v16, v10, v120, 0 op_sel:[0,0,0] op_sel_hi:[0,1,0]
	v_fma_mix_f32 v17, v11, v120, 0 op_sel:[0,1,0] op_sel_hi:[0,1,0]
	v_add_f32_dpp v20, v14, v14 quad_perm:[1,0,3,2] row_mask:0xf bank_mask:0xf bound_ctrl:1
	v_fma_mix_f32 v52, v13, v117, v52 op_sel:[0,1,0] op_sel_hi:[0,1,0]
	v_fma_mix_f32 v18, v12, v121, 0 op_sel:[0,0,0] op_sel_hi:[0,1,0]
	v_add_f32_dpp v20, v20, v20 quad_perm:[2,3,0,1] row_mask:0xf bank_mask:0xf bound_ctrl:1
	v_fma_mix_f32 v19, v13, v121, 0 op_sel:[0,1,0] op_sel_hi:[0,1,0]
	v_fma_mix_f32 v16, v130, v126, v16 op_sel:[0,0,0] op_sel_hi:[1,1,0]
	v_add_f32_dpp v20, v20, v20 row_half_mirror row_mask:0xf bank_mask:0xf bound_ctrl:1
	v_fma_mix_f32 v17, v130, v126, v17 op_sel:[0,1,0] op_sel_hi:[1,1,0]
	v_fma_mix_f32 v18, v130, v127, v18 op_sel:[0,0,0] op_sel_hi:[1,1,0]
	v_add_f32_dpp v20, v20, v20 row_mirror row_mask:0xf bank_mask:0xf bound_ctrl:1
	v_fma_mix_f32 v19, v130, v127, v19 op_sel:[0,1,0] op_sel_hi:[1,1,0]
	v_fma_mix_f32 v10, v20, v124, v16 op_sel:[0,0,0] op_sel_hi:[0,1,0]
	v_fma_mix_f32 v11, v20, v124, v17 op_sel:[0,1,0] op_sel_hi:[0,1,0]
	v_fma_mix_f32 v12, v20, v125, v18 op_sel:[0,0,0] op_sel_hi:[0,1,0]
	v_fma_mix_f32 v13, v20, v125, v19 op_sel:[0,1,0] op_sel_hi:[0,1,0]
	s_waitcnt lgkmcnt(4)
	ds_read_b64 v[24:25], v6 offset:7192
	ds_read_b128 v[26:29], v6 offset:7440
	ds_read_b128 v[30:33], v6 offset:7696
	ds_read_u16 v34, v7 offset:7184
	ds_read_b64 v[36:37], v6 offset:6168
	ds_read_b128 v[38:41], v6 offset:6416
	ds_read_b128 v[42:45], v6 offset:6672
	ds_read_u16 v46, v7 offset:6160
	v_fma_mix_f32 v14, v10, v134, 0 op_sel:[0,0,0] op_sel_hi:[0,1,0]
	v_fma_mix_f32 v53, v10, v128, 0 op_sel:[0,0,0] op_sel_hi:[0,1,0]
	v_fma_mix_f32 v14, v11, v134, v14 op_sel:[0,1,0] op_sel_hi:[0,1,0]
	v_fma_mix_f32 v53, v11, v128, v53 op_sel:[0,1,0] op_sel_hi:[0,1,0]
	v_fma_mix_f32 v14, v12, v135, v14 op_sel:[0,0,0] op_sel_hi:[0,1,0]
	v_fma_mix_f32 v53, v12, v129, v53 op_sel:[0,0,0] op_sel_hi:[0,1,0]
	v_fma_mix_f32 v14, v13, v135, v14 op_sel:[0,1,0] op_sel_hi:[0,1,0]
	v_fma_mix_f32 v16, v10, v132, 0 op_sel:[0,0,0] op_sel_hi:[0,1,0]
	v_fma_mix_f32 v17, v11, v132, 0 op_sel:[0,1,0] op_sel_hi:[0,1,0]
	v_add_f32_dpp v20, v14, v14 quad_perm:[1,0,3,2] row_mask:0xf bank_mask:0xf bound_ctrl:1
	v_fma_mix_f32 v53, v13, v129, v53 op_sel:[0,1,0] op_sel_hi:[0,1,0]
	v_fma_mix_f32 v18, v12, v133, 0 op_sel:[0,0,0] op_sel_hi:[0,1,0]
	v_add_f32_dpp v20, v20, v20 quad_perm:[2,3,0,1] row_mask:0xf bank_mask:0xf bound_ctrl:1
	v_fma_mix_f32 v19, v13, v133, 0 op_sel:[0,1,0] op_sel_hi:[0,1,0]
	v_fma_mix_f32 v16, v142, v138, v16 op_sel:[0,0,0] op_sel_hi:[1,1,0]
	v_add_f32_dpp v20, v20, v20 row_half_mirror row_mask:0xf bank_mask:0xf bound_ctrl:1
	v_fma_mix_f32 v17, v142, v138, v17 op_sel:[0,1,0] op_sel_hi:[1,1,0]
	v_fma_mix_f32 v18, v142, v139, v18 op_sel:[0,0,0] op_sel_hi:[1,1,0]
	v_add_f32_dpp v20, v20, v20 row_mirror row_mask:0xf bank_mask:0xf bound_ctrl:1
	v_fma_mix_f32 v19, v142, v139, v19 op_sel:[0,1,0] op_sel_hi:[1,1,0]
	v_fma_mix_f32 v10, v20, v136, v16 op_sel:[0,0,0] op_sel_hi:[0,1,0]
	v_fma_mix_f32 v11, v20, v136, v17 op_sel:[0,1,0] op_sel_hi:[0,1,0]
	v_fma_mix_f32 v12, v20, v137, v18 op_sel:[0,0,0] op_sel_hi:[0,1,0]
	v_fma_mix_f32 v13, v20, v137, v19 op_sel:[0,1,0] op_sel_hi:[0,1,0]
	s_waitcnt lgkmcnt(8)
	v_fma_mix_f32 v14, v10, v146, 0 op_sel:[0,0,0] op_sel_hi:[0,1,0]
	v_fma_mix_f32 v54, v10, v140, 0 op_sel:[0,0,0] op_sel_hi:[0,1,0]
	v_fma_mix_f32 v14, v11, v146, v14 op_sel:[0,1,0] op_sel_hi:[0,1,0]
	v_fma_mix_f32 v54, v11, v140, v54 op_sel:[0,1,0] op_sel_hi:[0,1,0]
	v_fma_mix_f32 v14, v12, v147, v14 op_sel:[0,0,0] op_sel_hi:[0,1,0]
	v_fma_mix_f32 v54, v12, v141, v54 op_sel:[0,0,0] op_sel_hi:[0,1,0]
	v_fma_mix_f32 v14, v13, v147, v14 op_sel:[0,1,0] op_sel_hi:[0,1,0]
	v_fma_mix_f32 v16, v10, v144, 0 op_sel:[0,0,0] op_sel_hi:[0,1,0]
	v_fma_mix_f32 v17, v11, v144, 0 op_sel:[0,1,0] op_sel_hi:[0,1,0]
	v_add_f32_dpp v20, v14, v14 quad_perm:[1,0,3,2] row_mask:0xf bank_mask:0xf bound_ctrl:1
	v_fma_mix_f32 v54, v13, v141, v54 op_sel:[0,1,0] op_sel_hi:[0,1,0]
	v_fma_mix_f32 v18, v12, v145, 0 op_sel:[0,0,0] op_sel_hi:[0,1,0]
	v_add_f32_dpp v20, v20, v20 quad_perm:[2,3,0,1] row_mask:0xf bank_mask:0xf bound_ctrl:1
	v_fma_mix_f32 v19, v13, v145, 0 op_sel:[0,1,0] op_sel_hi:[0,1,0]
	v_fma_mix_f32 v16, v154, v150, v16 op_sel:[0,0,0] op_sel_hi:[1,1,0]
	v_add_f32_dpp v20, v20, v20 row_half_mirror row_mask:0xf bank_mask:0xf bound_ctrl:1
	v_fma_mix_f32 v17, v154, v150, v17 op_sel:[0,1,0] op_sel_hi:[1,1,0]
	v_fma_mix_f32 v18, v154, v151, v18 op_sel:[0,0,0] op_sel_hi:[1,1,0]
	v_add_f32_dpp v20, v20, v20 row_mirror row_mask:0xf bank_mask:0xf bound_ctrl:1
	v_fma_mix_f32 v19, v154, v151, v19 op_sel:[0,1,0] op_sel_hi:[1,1,0]
	v_fma_mix_f32 v10, v20, v148, v16 op_sel:[0,0,0] op_sel_hi:[0,1,0]
	v_fma_mix_f32 v11, v20, v148, v17 op_sel:[0,1,0] op_sel_hi:[0,1,0]
	v_fma_mix_f32 v12, v20, v149, v18 op_sel:[0,0,0] op_sel_hi:[0,1,0]
	v_fma_mix_f32 v13, v20, v149, v19 op_sel:[0,1,0] op_sel_hi:[0,1,0]
	s_waitcnt lgkmcnt(4)
	ds_read_b64 v[72:73], v6 offset:5144
	ds_read_b128 v[74:77], v6 offset:5392
	ds_read_b128 v[78:81], v6 offset:5648
	ds_read_u16 v82, v7 offset:5136
	ds_read_b64 v[84:85], v6 offset:4120
	ds_read_b128 v[86:89], v6 offset:4368
	ds_read_b128 v[90:93], v6 offset:4624
	ds_read_u16 v94, v7 offset:4112
	v_fma_mix_f32 v14, v10, v26, 0 op_sel:[0,0,0] op_sel_hi:[0,1,0]
	v_fma_mix_f32 v55, v10, v152, 0 op_sel:[0,0,0] op_sel_hi:[0,1,0]
	v_fma_mix_f32 v14, v11, v26, v14 op_sel:[0,1,0] op_sel_hi:[0,1,0]
	v_fma_mix_f32 v55, v11, v152, v55 op_sel:[0,1,0] op_sel_hi:[0,1,0]
	v_fma_mix_f32 v14, v12, v27, v14 op_sel:[0,0,0] op_sel_hi:[0,1,0]
	v_fma_mix_f32 v55, v12, v153, v55 op_sel:[0,0,0] op_sel_hi:[0,1,0]
	v_fma_mix_f32 v14, v13, v27, v14 op_sel:[0,1,0] op_sel_hi:[0,1,0]
	v_fma_mix_f32 v16, v10, v24, 0 op_sel:[0,0,0] op_sel_hi:[0,1,0]
	v_fma_mix_f32 v17, v11, v24, 0 op_sel:[0,1,0] op_sel_hi:[0,1,0]
	v_add_f32_dpp v20, v14, v14 quad_perm:[1,0,3,2] row_mask:0xf bank_mask:0xf bound_ctrl:1
	v_fma_mix_f32 v55, v13, v153, v55 op_sel:[0,1,0] op_sel_hi:[0,1,0]
	v_fma_mix_f32 v18, v12, v25, 0 op_sel:[0,0,0] op_sel_hi:[0,1,0]
	v_add_f32_dpp v20, v20, v20 quad_perm:[2,3,0,1] row_mask:0xf bank_mask:0xf bound_ctrl:1
	v_fma_mix_f32 v19, v13, v25, 0 op_sel:[0,1,0] op_sel_hi:[0,1,0]
	v_fma_mix_f32 v16, v34, v30, v16 op_sel:[0,0,0] op_sel_hi:[1,1,0]
	v_add_f32_dpp v20, v20, v20 row_half_mirror row_mask:0xf bank_mask:0xf bound_ctrl:1
	v_fma_mix_f32 v17, v34, v30, v17 op_sel:[0,1,0] op_sel_hi:[1,1,0]
	v_fma_mix_f32 v18, v34, v31, v18 op_sel:[0,0,0] op_sel_hi:[1,1,0]
	v_add_f32_dpp v20, v20, v20 row_mirror row_mask:0xf bank_mask:0xf bound_ctrl:1
	v_fma_mix_f32 v19, v34, v31, v19 op_sel:[0,1,0] op_sel_hi:[1,1,0]
	v_fma_mix_f32 v10, v20, v28, v16 op_sel:[0,0,0] op_sel_hi:[0,1,0]
	v_fma_mix_f32 v11, v20, v28, v17 op_sel:[0,1,0] op_sel_hi:[0,1,0]
	v_fma_mix_f32 v12, v20, v29, v18 op_sel:[0,0,0] op_sel_hi:[0,1,0]
	v_fma_mix_f32 v13, v20, v29, v19 op_sel:[0,1,0] op_sel_hi:[0,1,0]
	s_waitcnt lgkmcnt(8)
	v_fma_mix_f32 v14, v10, v38, 0 op_sel:[0,0,0] op_sel_hi:[0,1,0]
	v_fma_mix_f32 v56, v10, v32, 0 op_sel:[0,0,0] op_sel_hi:[0,1,0]
	v_fma_mix_f32 v14, v11, v38, v14 op_sel:[0,1,0] op_sel_hi:[0,1,0]
	v_fma_mix_f32 v56, v11, v32, v56 op_sel:[0,1,0] op_sel_hi:[0,1,0]
	v_fma_mix_f32 v14, v12, v39, v14 op_sel:[0,0,0] op_sel_hi:[0,1,0]
	v_fma_mix_f32 v56, v12, v33, v56 op_sel:[0,0,0] op_sel_hi:[0,1,0]
	v_fma_mix_f32 v14, v13, v39, v14 op_sel:[0,1,0] op_sel_hi:[0,1,0]
	v_fma_mix_f32 v16, v10, v36, 0 op_sel:[0,0,0] op_sel_hi:[0,1,0]
	v_fma_mix_f32 v17, v11, v36, 0 op_sel:[0,1,0] op_sel_hi:[0,1,0]
	v_add_f32_dpp v20, v14, v14 quad_perm:[1,0,3,2] row_mask:0xf bank_mask:0xf bound_ctrl:1
	v_fma_mix_f32 v56, v13, v33, v56 op_sel:[0,1,0] op_sel_hi:[0,1,0]
	v_fma_mix_f32 v18, v12, v37, 0 op_sel:[0,0,0] op_sel_hi:[0,1,0]
	v_add_f32_dpp v20, v20, v20 quad_perm:[2,3,0,1] row_mask:0xf bank_mask:0xf bound_ctrl:1
	v_fma_mix_f32 v19, v13, v37, 0 op_sel:[0,1,0] op_sel_hi:[0,1,0]
	v_fma_mix_f32 v16, v46, v42, v16 op_sel:[0,0,0] op_sel_hi:[1,1,0]
	v_add_f32_dpp v20, v20, v20 row_half_mirror row_mask:0xf bank_mask:0xf bound_ctrl:1
	v_fma_mix_f32 v17, v46, v42, v17 op_sel:[0,1,0] op_sel_hi:[1,1,0]
	v_fma_mix_f32 v18, v46, v43, v18 op_sel:[0,0,0] op_sel_hi:[1,1,0]
	v_add_f32_dpp v20, v20, v20 row_mirror row_mask:0xf bank_mask:0xf bound_ctrl:1
	v_fma_mix_f32 v19, v46, v43, v19 op_sel:[0,1,0] op_sel_hi:[1,1,0]
	v_fma_mix_f32 v10, v20, v40, v16 op_sel:[0,0,0] op_sel_hi:[0,1,0]
	v_fma_mix_f32 v11, v20, v40, v17 op_sel:[0,1,0] op_sel_hi:[0,1,0]
	v_fma_mix_f32 v12, v20, v41, v18 op_sel:[0,0,0] op_sel_hi:[0,1,0]
	v_fma_mix_f32 v13, v20, v41, v19 op_sel:[0,1,0] op_sel_hi:[0,1,0]
	s_waitcnt lgkmcnt(4)
	ds_read_b64 v[108:109], v6 offset:3096
	ds_read_b128 v[110:113], v6 offset:3344
	ds_read_b128 v[114:117], v6 offset:3600
	ds_read_u16 v118, v7 offset:3088
	ds_read_b64 v[120:121], v6 offset:2072
	ds_read_b128 v[122:125], v6 offset:2320
	ds_read_b128 v[126:129], v6 offset:2576
	ds_read_u16 v130, v7 offset:2064
	v_fma_mix_f32 v14, v10, v74, 0 op_sel:[0,0,0] op_sel_hi:[0,1,0]
	v_fma_mix_f32 v57, v10, v44, 0 op_sel:[0,0,0] op_sel_hi:[0,1,0]
	v_fma_mix_f32 v14, v11, v74, v14 op_sel:[0,1,0] op_sel_hi:[0,1,0]
	v_fma_mix_f32 v57, v11, v44, v57 op_sel:[0,1,0] op_sel_hi:[0,1,0]
	v_fma_mix_f32 v14, v12, v75, v14 op_sel:[0,0,0] op_sel_hi:[0,1,0]
	v_fma_mix_f32 v57, v12, v45, v57 op_sel:[0,0,0] op_sel_hi:[0,1,0]
	v_fma_mix_f32 v14, v13, v75, v14 op_sel:[0,1,0] op_sel_hi:[0,1,0]
	v_fma_mix_f32 v16, v10, v72, 0 op_sel:[0,0,0] op_sel_hi:[0,1,0]
	v_fma_mix_f32 v17, v11, v72, 0 op_sel:[0,1,0] op_sel_hi:[0,1,0]
	v_add_f32_dpp v20, v14, v14 quad_perm:[1,0,3,2] row_mask:0xf bank_mask:0xf bound_ctrl:1
	v_fma_mix_f32 v57, v13, v45, v57 op_sel:[0,1,0] op_sel_hi:[0,1,0]
	v_fma_mix_f32 v18, v12, v73, 0 op_sel:[0,0,0] op_sel_hi:[0,1,0]
	v_add_f32_dpp v20, v20, v20 quad_perm:[2,3,0,1] row_mask:0xf bank_mask:0xf bound_ctrl:1
	v_fma_mix_f32 v19, v13, v73, 0 op_sel:[0,1,0] op_sel_hi:[0,1,0]
	v_fma_mix_f32 v16, v82, v78, v16 op_sel:[0,0,0] op_sel_hi:[1,1,0]
	v_add_f32_dpp v20, v20, v20 row_half_mirror row_mask:0xf bank_mask:0xf bound_ctrl:1
	v_fma_mix_f32 v17, v82, v78, v17 op_sel:[0,1,0] op_sel_hi:[1,1,0]
	v_fma_mix_f32 v18, v82, v79, v18 op_sel:[0,0,0] op_sel_hi:[1,1,0]
	v_add_f32_dpp v20, v20, v20 row_mirror row_mask:0xf bank_mask:0xf bound_ctrl:1
	v_fma_mix_f32 v19, v82, v79, v19 op_sel:[0,1,0] op_sel_hi:[1,1,0]
	v_fma_mix_f32 v10, v20, v76, v16 op_sel:[0,0,0] op_sel_hi:[0,1,0]
	v_fma_mix_f32 v11, v20, v76, v17 op_sel:[0,1,0] op_sel_hi:[0,1,0]
	v_fma_mix_f32 v12, v20, v77, v18 op_sel:[0,0,0] op_sel_hi:[0,1,0]
	v_fma_mix_f32 v13, v20, v77, v19 op_sel:[0,1,0] op_sel_hi:[0,1,0]
	s_waitcnt lgkmcnt(8)
	v_fma_mix_f32 v14, v10, v86, 0 op_sel:[0,0,0] op_sel_hi:[0,1,0]
	v_fma_mix_f32 v58, v10, v80, 0 op_sel:[0,0,0] op_sel_hi:[0,1,0]
	v_fma_mix_f32 v14, v11, v86, v14 op_sel:[0,1,0] op_sel_hi:[0,1,0]
	v_fma_mix_f32 v58, v11, v80, v58 op_sel:[0,1,0] op_sel_hi:[0,1,0]
	v_fma_mix_f32 v14, v12, v87, v14 op_sel:[0,0,0] op_sel_hi:[0,1,0]
	v_fma_mix_f32 v58, v12, v81, v58 op_sel:[0,0,0] op_sel_hi:[0,1,0]
	v_fma_mix_f32 v14, v13, v87, v14 op_sel:[0,1,0] op_sel_hi:[0,1,0]
	v_fma_mix_f32 v16, v10, v84, 0 op_sel:[0,0,0] op_sel_hi:[0,1,0]
	v_fma_mix_f32 v17, v11, v84, 0 op_sel:[0,1,0] op_sel_hi:[0,1,0]
	v_add_f32_dpp v20, v14, v14 quad_perm:[1,0,3,2] row_mask:0xf bank_mask:0xf bound_ctrl:1
	v_fma_mix_f32 v58, v13, v81, v58 op_sel:[0,1,0] op_sel_hi:[0,1,0]
	v_fma_mix_f32 v18, v12, v85, 0 op_sel:[0,0,0] op_sel_hi:[0,1,0]
	v_add_f32_dpp v20, v20, v20 quad_perm:[2,3,0,1] row_mask:0xf bank_mask:0xf bound_ctrl:1
	v_fma_mix_f32 v19, v13, v85, 0 op_sel:[0,1,0] op_sel_hi:[0,1,0]
	v_fma_mix_f32 v16, v94, v90, v16 op_sel:[0,0,0] op_sel_hi:[1,1,0]
	v_add_f32_dpp v20, v20, v20 row_half_mirror row_mask:0xf bank_mask:0xf bound_ctrl:1
	v_fma_mix_f32 v17, v94, v90, v17 op_sel:[0,1,0] op_sel_hi:[1,1,0]
	v_fma_mix_f32 v18, v94, v91, v18 op_sel:[0,0,0] op_sel_hi:[1,1,0]
	v_add_f32_dpp v20, v20, v20 row_mirror row_mask:0xf bank_mask:0xf bound_ctrl:1
	v_fma_mix_f32 v19, v94, v91, v19 op_sel:[0,1,0] op_sel_hi:[1,1,0]
	v_fma_mix_f32 v10, v20, v88, v16 op_sel:[0,0,0] op_sel_hi:[0,1,0]
	v_fma_mix_f32 v11, v20, v88, v17 op_sel:[0,1,0] op_sel_hi:[0,1,0]
	v_fma_mix_f32 v12, v20, v89, v18 op_sel:[0,0,0] op_sel_hi:[0,1,0]
	v_fma_mix_f32 v13, v20, v89, v19 op_sel:[0,1,0] op_sel_hi:[0,1,0]
	s_waitcnt lgkmcnt(4)
	ds_read_b64 v[132:133], v6 offset:1048
	ds_read_b128 v[134:137], v6 offset:1296
	ds_read_b128 v[138:141], v6 offset:1552
	ds_read_u16 v142, v7 offset:1040
	ds_read_b64 v[144:145], v6 offset:24
	ds_read_b128 v[146:149], v6 offset:272
	ds_read_b128 v[150:153], v6 offset:528
	ds_read_u16 v154, v7 offset:16
	v_fma_mix_f32 v14, v10, v110, 0 op_sel:[0,0,0] op_sel_hi:[0,1,0]
	v_fma_mix_f32 v59, v10, v92, 0 op_sel:[0,0,0] op_sel_hi:[0,1,0]
	v_fma_mix_f32 v14, v11, v110, v14 op_sel:[0,1,0] op_sel_hi:[0,1,0]
	v_fma_mix_f32 v59, v11, v92, v59 op_sel:[0,1,0] op_sel_hi:[0,1,0]
	v_fma_mix_f32 v14, v12, v111, v14 op_sel:[0,0,0] op_sel_hi:[0,1,0]
	v_fma_mix_f32 v59, v12, v93, v59 op_sel:[0,0,0] op_sel_hi:[0,1,0]
	v_fma_mix_f32 v14, v13, v111, v14 op_sel:[0,1,0] op_sel_hi:[0,1,0]
	v_fma_mix_f32 v16, v10, v108, 0 op_sel:[0,0,0] op_sel_hi:[0,1,0]
	v_fma_mix_f32 v17, v11, v108, 0 op_sel:[0,1,0] op_sel_hi:[0,1,0]
	v_add_f32_dpp v20, v14, v14 quad_perm:[1,0,3,2] row_mask:0xf bank_mask:0xf bound_ctrl:1
	v_fma_mix_f32 v59, v13, v93, v59 op_sel:[0,1,0] op_sel_hi:[0,1,0]
	v_fma_mix_f32 v18, v12, v109, 0 op_sel:[0,0,0] op_sel_hi:[0,1,0]
	v_add_f32_dpp v20, v20, v20 quad_perm:[2,3,0,1] row_mask:0xf bank_mask:0xf bound_ctrl:1
	v_fma_mix_f32 v19, v13, v109, 0 op_sel:[0,1,0] op_sel_hi:[0,1,0]
	v_fma_mix_f32 v16, v118, v114, v16 op_sel:[0,0,0] op_sel_hi:[1,1,0]
	v_add_f32_dpp v20, v20, v20 row_half_mirror row_mask:0xf bank_mask:0xf bound_ctrl:1
	v_fma_mix_f32 v17, v118, v114, v17 op_sel:[0,1,0] op_sel_hi:[1,1,0]
	v_fma_mix_f32 v18, v118, v115, v18 op_sel:[0,0,0] op_sel_hi:[1,1,0]
	v_add_f32_dpp v20, v20, v20 row_mirror row_mask:0xf bank_mask:0xf bound_ctrl:1
	v_fma_mix_f32 v19, v118, v115, v19 op_sel:[0,1,0] op_sel_hi:[1,1,0]
	v_fma_mix_f32 v10, v20, v112, v16 op_sel:[0,0,0] op_sel_hi:[0,1,0]
	v_fma_mix_f32 v11, v20, v112, v17 op_sel:[0,1,0] op_sel_hi:[0,1,0]
	v_fma_mix_f32 v12, v20, v113, v18 op_sel:[0,0,0] op_sel_hi:[0,1,0]
	v_fma_mix_f32 v13, v20, v113, v19 op_sel:[0,1,0] op_sel_hi:[0,1,0]
	s_waitcnt lgkmcnt(8)
; DEVINL u16 f2bf(float a) { return (u16)(pk2(a, 0.f) & 0xffffu); }
; #define RW_LANDED(WN, XN, KN, VN) asm volatile("s_waitcnt lgkmcnt(0)" : "+v"(WN), "+v"(XN), "+v"(KN), "+v"(VN) :: "memory")
; #define RW_STEP2(B) RW_STEP(B, WvA, XA, KrA, vhA, WvB, XB, KrB, vhB); RW_STEP((B) + 1, WvB, XB, KrB, vhB, WvA, XA, KrA, vhA)
; #define RW_STEP4(B) RW_STEP2(B); RW_STEP2((B) + 2)
; #define RW_DMA4(B) RW_DMA_ONLY(B); RW_DMA_ONLY((B) + 1); RW_DMA_ONLY((B) + 2); RW_DMA_ONLY((B) + 3)
; template <int DIR>
; DEVINL void rwkv_scan_dir(const Params& p, int task, int lane, int wave) {
;     ...
;   u32x2 WvA, WvB; u32x4 XA, XB, KrA, KrB; unsigned vhA, vhB;
;   RW_DMA4(0); RW_DMA4(4); RW_DMA4(8); RW_DMA4(12); RW_DMA4(16); RW_DMA4(20);
;   RW_READ(0, WvA, XA, KrA, vhA, 23);
;   RW_LANDED(WvA, XA, KrA, vhA);
;   float ypart = 0.f;
; #pragma unroll 1
;   for (int st = 0; st < 4096; st += 32) {
;     RW_STEP(0, WvA, XA, KrA, vhA, WvB, XB, KrB, vhB);
;     if (st > 0) { const int q0 = st - 16 + seg; yo[(long)(DIR ? (4095 - q0) : q0) * 1024] = f2bf(ykeep); }
;     RW_STEP(1, WvB, XB, KrB, vhB, WvA, XA, KrA, vhA);
;     RW_STEP2(2); RW_STEP4(4); RW_STEP4(8); RW_STEP4(12);
;     RW_STEP(16, WvA, XA, KrA, vhA, WvB, XB, KrB, vhB);
;     { const int q0 = st + seg; yo[(long)(DIR ? (4095 - q0) : q0) * 1024] = f2bf(ykeep); }
;     RW_STEP(17, WvB, XB, KrB, vhB, WvA, XA, KrA, vhA);
;     RW_STEP2(18); RW_STEP4(20); RW_STEP4(24); RW_STEP4(28);
;   }
	ds_read_b128 v[100:103], v9
	ds_read_b128 v[104:107], v9 offset:16
	v_fma_mix_f32 v14, v10, v122, 0 op_sel:[0,0,0] op_sel_hi:[0,1,0]
	v_fma_mix_f32 v60, v10, v116, 0 op_sel:[0,0,0] op_sel_hi:[0,1,0]
	v_fma_mix_f32 v14, v11, v122, v14 op_sel:[0,1,0] op_sel_hi:[0,1,0]
	v_fma_mix_f32 v60, v11, v116, v60 op_sel:[0,1,0] op_sel_hi:[0,1,0]
	v_fma_mix_f32 v14, v12, v123, v14 op_sel:[0,0,0] op_sel_hi:[0,1,0]
	v_fma_mix_f32 v60, v12, v117, v60 op_sel:[0,0,0] op_sel_hi:[0,1,0]
	v_fma_mix_f32 v14, v13, v123, v14 op_sel:[0,1,0] op_sel_hi:[0,1,0]
	v_fma_mix_f32 v16, v10, v120, 0 op_sel:[0,0,0] op_sel_hi:[0,1,0]
	v_fma_mix_f32 v17, v11, v120, 0 op_sel:[0,1,0] op_sel_hi:[0,1,0]
	v_add_f32_dpp v20, v14, v14 quad_perm:[1,0,3,2] row_mask:0xf bank_mask:0xf bound_ctrl:1
	v_fma_mix_f32 v60, v13, v117, v60 op_sel:[0,1,0] op_sel_hi:[0,1,0]
	v_fma_mix_f32 v18, v12, v121, 0 op_sel:[0,0,0] op_sel_hi:[0,1,0]
	v_add_f32_dpp v20, v20, v20 quad_perm:[2,3,0,1] row_mask:0xf bank_mask:0xf bound_ctrl:1
	v_fma_mix_f32 v19, v13, v121, 0 op_sel:[0,1,0] op_sel_hi:[0,1,0]
	v_fma_mix_f32 v16, v130, v126, v16 op_sel:[0,0,0] op_sel_hi:[1,1,0]
	v_add_f32_dpp v20, v20, v20 row_half_mirror row_mask:0xf bank_mask:0xf bound_ctrl:1
	v_fma_mix_f32 v17, v130, v126, v17 op_sel:[0,1,0] op_sel_hi:[1,1,0]
	v_fma_mix_f32 v18, v130, v127, v18 op_sel:[0,0,0] op_sel_hi:[1,1,0]
	v_add_f32_dpp v20, v20, v20 row_mirror row_mask:0xf bank_mask:0xf bound_ctrl:1
	v_fma_mix_f32 v19, v130, v127, v19 op_sel:[0,1,0] op_sel_hi:[1,1,0]
	v_fma_mix_f32 v10, v20, v124, v16 op_sel:[0,0,0] op_sel_hi:[0,1,0]
	v_fma_mix_f32 v11, v20, v124, v17 op_sel:[0,1,0] op_sel_hi:[0,1,0]
	v_fma_mix_f32 v12, v20, v125, v18 op_sel:[0,0,0] op_sel_hi:[0,1,0]
	v_fma_mix_f32 v13, v20, v125, v19 op_sel:[0,1,0] op_sel_hi:[0,1,0]
	s_waitcnt lgkmcnt(6)
	v_add_u32_e32 v6, 0xffffc000, v6
	v_add_u32_e32 v7, 0xffffc000, v7
	v_and_b32_e32 v6, 0x1ffff, v6
	v_and_b32_e32 v7, 0x1ffff, v7
	ds_read_b64 v[24:25], v6 offset:15384
	ds_read_b128 v[26:29], v6 offset:15632
	ds_read_b128 v[30:33], v6 offset:15888
	ds_read_u16 v34, v7 offset:15376
	ds_read_b64 v[36:37], v6 offset:14360
	ds_read_b128 v[38:41], v6 offset:14608
	ds_read_b128 v[42:45], v6 offset:14864
	ds_read_u16 v46, v7 offset:14352
	v_fma_mix_f32 v14, v10, v134, 0 op_sel:[0,0,0] op_sel_hi:[0,1,0]
	v_fma_mix_f32 v61, v10, v128, 0 op_sel:[0,0,0] op_sel_hi:[0,1,0]
	v_fma_mix_f32 v14, v11, v134, v14 op_sel:[0,1,0] op_sel_hi:[0,1,0]
	v_fma_mix_f32 v61, v11, v128, v61 op_sel:[0,1,0] op_sel_hi:[0,1,0]
	v_fma_mix_f32 v14, v12, v135, v14 op_sel:[0,0,0] op_sel_hi:[0,1,0]
	v_fma_mix_f32 v61, v12, v129, v61 op_sel:[0,0,0] op_sel_hi:[0,1,0]
	v_fma_mix_f32 v14, v13, v135, v14 op_sel:[0,1,0] op_sel_hi:[0,1,0]
	v_fma_mix_f32 v16, v10, v132, 0 op_sel:[0,0,0] op_sel_hi:[0,1,0]
	v_fma_mix_f32 v17, v11, v132, 0 op_sel:[0,1,0] op_sel_hi:[0,1,0]
	v_add_f32_dpp v20, v14, v14 quad_perm:[1,0,3,2] row_mask:0xf bank_mask:0xf bound_ctrl:1
	v_fma_mix_f32 v61, v13, v129, v61 op_sel:[0,1,0] op_sel_hi:[0,1,0]
	v_fma_mix_f32 v18, v12, v133, 0 op_sel:[0,0,0] op_sel_hi:[0,1,0]
	v_add_f32_dpp v20, v20, v20 quad_perm:[2,3,0,1] row_mask:0xf bank_mask:0xf bound_ctrl:1
	v_fma_mix_f32 v19, v13, v133, 0 op_sel:[0,1,0] op_sel_hi:[0,1,0]
	v_fma_mix_f32 v16, v142, v138, v16 op_sel:[0,0,0] op_sel_hi:[1,1,0]
	v_add_f32_dpp v20, v20, v20 row_half_mirror row_mask:0xf bank_mask:0xf bound_ctrl:1
	v_fma_mix_f32 v17, v142, v138, v17 op_sel:[0,1,0] op_sel_hi:[1,1,0]
	v_fma_mix_f32 v18, v142, v139, v18 op_sel:[0,0,0] op_sel_hi:[1,1,0]
	v_add_f32_dpp v20, v20, v20 row_mirror row_mask:0xf bank_mask:0xf bound_ctrl:1
	v_fma_mix_f32 v19, v142, v139, v19 op_sel:[0,1,0] op_sel_hi:[1,1,0]
	v_fma_mix_f32 v10, v20, v136, v16 op_sel:[0,0,0] op_sel_hi:[0,1,0]
	v_fma_mix_f32 v11, v20, v136, v17 op_sel:[0,1,0] op_sel_hi:[0,1,0]
	v_fma_mix_f32 v12, v20, v137, v18 op_sel:[0,0,0] op_sel_hi:[0,1,0]
	v_fma_mix_f32 v13, v20, v137, v19 op_sel:[0,1,0] op_sel_hi:[0,1,0]
	s_waitcnt lgkmcnt(8)
	v_fma_mix_f32 v14, v10, v146, 0 op_sel:[0,0,0] op_sel_hi:[0,1,0]
	v_fma_mix_f32 v62, v10, v140, 0 op_sel:[0,0,0] op_sel_hi:[0,1,0]
	v_fma_mix_f32 v14, v11, v146, v14 op_sel:[0,1,0] op_sel_hi:[0,1,0]
	v_fma_mix_f32 v62, v11, v140, v62 op_sel:[0,1,0] op_sel_hi:[0,1,0]
	v_fma_mix_f32 v14, v12, v147, v14 op_sel:[0,0,0] op_sel_hi:[0,1,0]
	v_fma_mix_f32 v62, v12, v141, v62 op_sel:[0,0,0] op_sel_hi:[0,1,0]
	v_fma_mix_f32 v14, v13, v147, v14 op_sel:[0,1,0] op_sel_hi:[0,1,0]
	v_fma_mix_f32 v16, v10, v144, 0 op_sel:[0,0,0] op_sel_hi:[0,1,0]
	v_fma_mix_f32 v17, v11, v144, 0 op_sel:[0,1,0] op_sel_hi:[0,1,0]
	v_add_f32_dpp v20, v14, v14 quad_perm:[1,0,3,2] row_mask:0xf bank_mask:0xf bound_ctrl:1
	v_fma_mix_f32 v62, v13, v141, v62 op_sel:[0,1,0] op_sel_hi:[0,1,0]
	v_fma_mix_f32 v18, v12, v145, 0 op_sel:[0,0,0] op_sel_hi:[0,1,0]
	v_add_f32_dpp v20, v20, v20 quad_perm:[2,3,0,1] row_mask:0xf bank_mask:0xf bound_ctrl:1
	v_fma_mix_f32 v19, v13, v145, 0 op_sel:[0,1,0] op_sel_hi:[0,1,0]
	v_fma_mix_f32 v16, v154, v150, v16 op_sel:[0,0,0] op_sel_hi:[1,1,0]
	v_add_f32_dpp v20, v20, v20 row_half_mirror row_mask:0xf bank_mask:0xf bound_ctrl:1
	v_fma_mix_f32 v17, v154, v150, v17 op_sel:[0,1,0] op_sel_hi:[1,1,0]
	v_fma_mix_f32 v18, v154, v151, v18 op_sel:[0,0,0] op_sel_hi:[1,1,0]
	v_add_f32_dpp v20, v20, v20 row_mirror row_mask:0xf bank_mask:0xf bound_ctrl:1
	v_fma_mix_f32 v19, v154, v151, v19 op_sel:[0,1,0] op_sel_hi:[1,1,0]
	v_fma_mix_f32 v10, v20, v148, v16 op_sel:[0,0,0] op_sel_hi:[0,1,0]
	v_fma_mix_f32 v11, v20, v148, v17 op_sel:[0,1,0] op_sel_hi:[0,1,0]
	v_fma_mix_f32 v12, v20, v149, v18 op_sel:[0,0,0] op_sel_hi:[0,1,0]
	v_fma_mix_f32 v13, v20, v149, v19 op_sel:[0,1,0] op_sel_hi:[0,1,0]
	s_waitcnt lgkmcnt(4)
	s_add_u32 s15, s15, 1
	s_add_u32 s14, s14, 1
	v_mov_b32_e32 v69, s15
	ds_write_b32 v68, v69
	s_cmp_lt_u32 s14, 0x100
	s_cbranch_scc1 .Lrw_blk_d1
; DEVINL u16 f2bf(float a) { return (u16)(pk2(a, 0.f) & 0xffffu); }
; template <int DIR>
; DEVINL void rwkv_scan_dir(const Params& p, int task, int lane, int wave) {
;     ...
;   {
;     const float ylast = allred16(ypart);
;     ykeep = (seg == 15) ? ylast : ykeep;
;     const int q0 = 4096 - 16 + seg; yo[(long)(DIR ? (4095 - q0) : q0) * 1024] = f2bf(ykeep);
;   }
	v_fma_mix_f32 v21, v10, v152, 0 op_sel:[0,0,0] op_sel_hi:[0,1,0]
	v_fma_mix_f32 v22, v12, v153, 0 op_sel:[0,0,0] op_sel_hi:[0,1,0]
	v_fma_mix_f32 v21, v11, v152, v21 op_sel:[0,1,0] op_sel_hi:[0,1,0]
	v_fma_mix_f32 v22, v13, v153, v22 op_sel:[0,1,0] op_sel_hi:[0,1,0]
	v_add_f32_e32 v63, v21, v22
	s_nop 1
	v_add_f32_dpp v48, v48, v48 row_ror:8 row_mask:0xf bank_mask:0x3
	v_add_f32_dpp v49, v49, v49 row_ror:8 row_mask:0xf bank_mask:0x3
	v_add_f32_dpp v50, v50, v50 row_ror:8 row_mask:0xf bank_mask:0x3
	v_add_f32_dpp v51, v51, v51 row_ror:8 row_mask:0xf bank_mask:0x3
	v_add_f32_dpp v52, v52, v52 row_ror:8 row_mask:0xf bank_mask:0x3
	v_add_f32_dpp v53, v53, v53 row_ror:8 row_mask:0xf bank_mask:0x3
	v_add_f32_dpp v54, v54, v54 row_ror:8 row_mask:0xf bank_mask:0x3
	v_add_f32_dpp v55, v55, v55 row_ror:8 row_mask:0xf bank_mask:0x3
	v_add_f32_dpp v48, v56, v56 row_ror:8 row_mask:0xf bank_mask:0xc
	v_add_f32_dpp v49, v57, v57 row_ror:8 row_mask:0xf bank_mask:0xc
	v_add_f32_dpp v50, v58, v58 row_ror:8 row_mask:0xf bank_mask:0xc
	v_add_f32_dpp v51, v59, v59 row_ror:8 row_mask:0xf bank_mask:0xc
	v_add_f32_dpp v52, v60, v60 row_ror:8 row_mask:0xf bank_mask:0xc
	v_add_f32_dpp v53, v61, v61 row_ror:8 row_mask:0xf bank_mask:0xc
	v_add_f32_dpp v54, v62, v62 row_ror:8 row_mask:0xf bank_mask:0xc
	v_add_f32_dpp v55, v63, v63 row_ror:8 row_mask:0xf bank_mask:0xc
	v_add_f32_dpp v48, v48, v48 row_ror:12 row_mask:0xf bank_mask:0x5
	v_add_f32_dpp v49, v49, v49 row_ror:12 row_mask:0xf bank_mask:0x5
	v_add_f32_dpp v50, v50, v50 row_ror:12 row_mask:0xf bank_mask:0x5
	v_add_f32_dpp v51, v51, v51 row_ror:12 row_mask:0xf bank_mask:0x5
	v_add_f32_dpp v48, v52, v52 row_ror:4 row_mask:0xf bank_mask:0xa
	v_add_f32_dpp v49, v53, v53 row_ror:4 row_mask:0xf bank_mask:0xa
	v_add_f32_dpp v50, v54, v54 row_ror:4 row_mask:0xf bank_mask:0xa
	v_add_f32_dpp v51, v55, v55 row_ror:4 row_mask:0xf bank_mask:0xa
	v_add_f32_dpp v64, v48, v48 quad_perm:[2,3,0,1] row_mask:0xf bank_mask:0xf bound_ctrl:1
	v_add_f32_dpp v65, v50, v50 quad_perm:[2,3,0,1] row_mask:0xf bank_mask:0xf bound_ctrl:1
	v_cndmask_b32_e64 v56, v64, v65, s[50:51]
	v_add_f32_dpp v64, v49, v49 quad_perm:[2,3,0,1] row_mask:0xf bank_mask:0xf bound_ctrl:1
	v_add_f32_dpp v65, v51, v51 quad_perm:[2,3,0,1] row_mask:0xf bank_mask:0xf bound_ctrl:1
	v_cndmask_b32_e64 v57, v64, v65, s[50:51]
	v_add_f32_dpp v64, v56, v56 quad_perm:[1,0,3,2] row_mask:0xf bank_mask:0xf bound_ctrl:1
	s_nop 0
	v_add_f32_dpp v65, v57, v57 quad_perm:[1,0,3,2] row_mask:0xf bank_mask:0xf bound_ctrl:1
	v_cndmask_b32_e64 v66, v64, v65, s[48:49]
	v_cvt_pk_bf16_f32 v66, v66, v66
	global_store_short v8, v66, s[12:13]
	s_sub_u32 s12, s12, 0x8000
	s_subb_u32 s13, s13, 0
